# bundle on late-barrier version: P1b gate-bias prefetch before K-loop (no epilogue-start drain), SchedA all 16 gate loads issued up-front, P2 sample tasks done by WGs 0-127 only
# speedup vs baseline: 1.0092x; 1.0092x over previous
; __device__ __forceinline__ void phase2(const Params& p) {
;     ...
;     const int NT = gridDim.x * NTHREADS, gt = blockIdx.x * NTHREADS + t_;
;     for (int id = gt; id < 131072; id += NT) { const int cg8 = id & 127, run = id >> 7; stencil_run<false>(p, run >> 8, (run & 255) * 32, 32, cg8 * 8); }
;     for (int id = gt; id < 131072; id += NT) { const int cg8 = id & 127, run = id >> 7; stencil_run<true>(p, run >> 5, (run & 31) * 2, 2, cg8 * 8); }
.LBB0_706:
	s_or_b64 exec, exec, s[18:19]
	s_cmpk_gt_i32 s8, 0x7f
	s_cbranch_scc1 .LBB0_726
	s_mov_b32 s31, 0x10000
	s_add_u32 s18, s26, 0x19620000
	s_addc_u32 s19, s27, 0
	s_add_u32 s20, s26, 0x2ea20000
	s_addc_u32 s21, s27, 0
	s_mov_b64 s[34:35], 0
	v_mov_b32_e32 v75, 0
	s_mov_b64 s[40:41], 0x1000
	s_mov_b64 s[44:45], 0x2000
	s_movk_i32 s52, 0x1000
	s_movk_i32 s53, 0x1080
	s_mov_b32 s54, 0x1ffff
	s_branch .LBB0_708

; template <int MODE  , class Epi, class Sched>
; __device__ __forceinline__ void gemm_phase(LAS unsigned char* lds, const GemmDesc g, const Sched& S, const Epi& E) {
;     ...
;         if (zero) {
; #pragma unroll
;             for (int a = 0; a < 2; ++a)
; #pragma unroll
;                 for (int b = 0; b < 2; ++b)
; #pragma unroll
;                     for (int m = 0; m < 4; ++m)
; #pragma unroll
;                         for (int n = 0; n < 2; ++n) acc[a][b][m][n] = (f32x4){0.f, 0.f, 0.f, 0.f};
;         }
;     __device__ __forceinline__ bool operator()(f32x4 (&acc)[2][2][4][2], const Unit& u, int wr, int wc, int fr, int fq) const {
;     ...
;             const int ch0 = (pn - 24) * 128 + cl;
;             const f32x4 ba0 = *(const f32x4*)(bgate + ch0), ba1 = *(const f32x4*)(bgate + ch0 + 4), bb0 = *(const f32x4*)(bgate + D + ch0), bb1 = *(const f32x4*)(bgate + D + ch0 + 4);
.LBB0_736:
	s_add_u32 s77, s46, 0x100
	v_mov_b32_e32 v18, 0
	s_addc_u32 s78, s47, 0
	s_mov_b32 s79, -2
	v_lshl_add_u32 v200, s76, 7, v167
	v_ashrrev_i32_e32 v201, 31, v200
	v_lshlrev_b64 v[200:201], 2, v[200:201]
	v_lshl_add_u64 v[202:203], s[48:49], 0, v[200:201]
	v_lshl_add_u64 v[200:201], s[16:17], 0, v[200:201]
	global_load_dwordx4 v[232:235], v[202:203], off
	global_load_dwordx4 v[236:239], v[200:201], off
	global_load_dwordx4 v[240:243], v[202:203], off offset:16
	global_load_dwordx4 v[244:247], v[200:201], off offset:16
	v_mov_b32_e32 v19, v18
	v_mov_b64_e32 v[20:21], v[18:19]
	v_mov_b64_e32 v[22:23], v[18:19]
	v_mov_b64_e32 v[24:25], v[18:19]
	v_mov_b64_e32 v[34:35], v[18:19]
	v_mov_b64_e32 v[36:37], v[18:19]
	v_mov_b64_e32 v[38:39], v[18:19]
	v_mov_b64_e32 v[40:41], v[18:19]
	v_mov_b64_e32 v[50:51], v[18:19]
	v_mov_b64_e32 v[52:53], v[18:19]
	v_mov_b64_e32 v[54:55], v[18:19]
	v_mov_b64_e32 v[56:57], v[18:19]
	v_mov_b64_e32 v[66:67], v[18:19]
	v_mov_b64_e32 v[68:69], v[18:19]
	v_mov_b64_e32 v[70:71], v[18:19]
	v_mov_b64_e32 v[72:73], v[18:19]
	v_mov_b64_e32 v[26:27], v[18:19]
	v_mov_b64_e32 v[28:29], v[18:19]
	v_mov_b64_e32 v[30:31], v[18:19]
	v_mov_b64_e32 v[32:33], v[18:19]
	v_mov_b64_e32 v[42:43], v[18:19]
	v_mov_b64_e32 v[44:45], v[18:19]
	v_mov_b64_e32 v[46:47], v[18:19]
	v_mov_b64_e32 v[48:49], v[18:19]
	v_mov_b64_e32 v[58:59], v[18:19]
	v_mov_b64_e32 v[60:61], v[18:19]
	v_mov_b64_e32 v[62:63], v[18:19]
	v_mov_b64_e32 v[64:65], v[18:19]
	v_mov_b64_e32 v[74:75], v[18:19]
	v_mov_b64_e32 v[76:77], v[18:19]
	v_mov_b64_e32 v[78:79], v[18:19]
	v_mov_b64_e32 v[80:81], v[18:19]
	v_mov_b64_e32 v[82:83], v[18:19]
	v_mov_b64_e32 v[84:85], v[18:19]
	v_mov_b64_e32 v[86:87], v[18:19]
	v_mov_b64_e32 v[88:89], v[18:19]
	v_mov_b64_e32 v[98:99], v[18:19]
	v_mov_b64_e32 v[100:101], v[18:19]
	v_mov_b64_e32 v[102:103], v[18:19]
	v_mov_b64_e32 v[104:105], v[18:19]
	v_mov_b64_e32 v[114:115], v[18:19]
	v_mov_b64_e32 v[116:117], v[18:19]
	v_mov_b64_e32 v[118:119], v[18:19]
	v_mov_b64_e32 v[120:121], v[18:19]
	v_mov_b64_e32 v[130:131], v[18:19]
	v_mov_b64_e32 v[132:133], v[18:19]
	v_mov_b64_e32 v[134:135], v[18:19]
	v_mov_b64_e32 v[136:137], v[18:19]
	v_mov_b64_e32 v[90:91], v[18:19]
	v_mov_b64_e32 v[92:93], v[18:19]
	v_mov_b64_e32 v[94:95], v[18:19]
	v_mov_b64_e32 v[96:97], v[18:19]
	v_mov_b64_e32 v[106:107], v[18:19]
	v_mov_b64_e32 v[108:109], v[18:19]
	v_mov_b64_e32 v[110:111], v[18:19]
	v_mov_b64_e32 v[112:113], v[18:19]
	v_mov_b64_e32 v[122:123], v[18:19]
	v_mov_b64_e32 v[124:125], v[18:19]
	v_mov_b64_e32 v[126:127], v[18:19]
	v_mov_b64_e32 v[128:129], v[18:19]
	v_mov_b64_e32 v[138:139], v[18:19]
	v_mov_b64_e32 v[140:141], v[18:19]
	v_mov_b64_e32 v[142:143], v[18:19]
	v_mov_b64_e32 v[144:145], v[18:19]
	s_cmp_eq_u32 s101, 1
	s_cbranch_scc0 .Lnodb_p1b
	s_barrier
	s_mov_b32 s101, 0

; __device__ __forceinline__ unsigned pk_bf16(float lo, float hi) { const f32x2_t v = {lo, hi}; return __builtin_bit_cast(unsigned, __builtin_convertvector(v, bf16x2_t)); }
;     __device__ __forceinline__ bool operator()(f32x4 (&acc)[2][2][4][2], const Unit& u, int wr, int wc, int fr, int fq) const {
;     ...
;                 for (int m = 0; m < 4; ++m) { const int row = r0 + ai * HALF + m * 16;
;                     const f32x4 a0 = acc[ai][0][m][0] * gsc + ba0, a1 = acc[ai][0][m][1] * gsc + ba1, b0 = acc[ai][1][m][0] * gsc + bb0, b1 = acc[ai][1][m][1] * gsc + bb1;
;                     f32x4 r0v, r1v, s0v, s1v;
; #pragma unroll
;                     for (int j = 0; j < 4; ++j) {
;                         const float ea0 = __builtin_amdgcn_exp2f(-1.44269504f * fminf(fmaxf(a0[j], -40.f), 40.f)), eb0 = __builtin_amdgcn_exp2f(-1.44269504f * fminf(fmaxf(b0[j], -40.f), 40.f));
;                         const float ea1 = __builtin_amdgcn_exp2f(-1.44269504f * fminf(fmaxf(a1[j], -40.f), 40.f)), eb1 = __builtin_amdgcn_exp2f(-1.44269504f * fminf(fmaxf(b1[j], -40.f), 40.f));
;                         s0v[j] = __builtin_amdgcn_rcpf(1.0f + eb0); s1v[j] = __builtin_amdgcn_rcpf(1.0f + eb1);
;                         r0v[j] = (1.0f + eb0) * __builtin_amdgcn_rcpf(1.0f + ea0); r1v[j] = (1.0f + eb1) * __builtin_amdgcn_rcpf(1.0f + ea1); }
;                     u32x4 w; w.x = pk_bf16(r0v[0], r0v[1]); w.y = pk_bf16(r0v[2], r0v[3]); w.z = pk_bf16(r1v[0], r1v[1]); w.w = pk_bf16(r1v[2], r1v[3]);
;                     *(u32x4*)(SGR + (size_t)row * D + ch0) = w;
.Lkepi_p1b:
	v_lshl_add_u32 v160, s76, 7, v167
	v_ashrrev_i32_e32 v161, 31, v160
	v_lshlrev_b64 v[2:3], 2, v[160:161]
	s_nop 15
	s_nop 15
	v_lshl_add_u32 v158, s75, 8, v1
	s_and_b64 vcc, exec, s[42:43]
	s_mov_b32 s76, s73
	s_mov_b32 s75, s72
	s_mov_b64 s[46:47], s[2:3]
	s_mov_b64 s[50:51], s[44:45]
	s_nop 0
	v_fmamk_f32 v134, v134, 0x3c800000, v236
	v_fmamk_f32 v142, v142, 0x3c800000, v232
	v_fmamk_f32 v138, v138, 0x3c800000, v240
	v_fmamk_f32 v143, v143, 0x3c800000, v233
	v_fmamk_f32 v144, v144, 0x3c800000, v234
	v_fmamk_f32 v145, v145, 0x3c800000, v235
	v_fmamk_f32 v139, v139, 0x3c800000, v241
	v_fmamk_f32 v140, v140, 0x3c800000, v242
	v_med3_f32 v142, v142, s71, v172
	v_med3_f32 v138, v138, s71, v172
	v_med3_f32 v143, v143, s71, v172
	v_med3_f32 v144, v144, s71, v172
	v_med3_f32 v145, v145, s71, v172
	v_med3_f32 v139, v139, s71, v172
	v_med3_f32 v140, v140, s71, v172
	v_mul_f32_e32 v142, 0xbfb8aa3b, v142
	v_mul_f32_e32 v138, 0xbfb8aa3b, v138
	v_mul_f32_e32 v143, 0xbfb8aa3b, v143
	v_mul_f32_e32 v144, 0xbfb8aa3b, v144
	v_mul_f32_e32 v145, 0xbfb8aa3b, v145
	v_mul_f32_e32 v139, 0xbfb8aa3b, v139
	v_mul_f32_e32 v140, 0xbfb8aa3b, v140
	v_exp_f32_e32 v142, v142
	v_exp_f32_e32 v138, v138
	v_exp_f32_e32 v143, v143
	v_exp_f32_e32 v144, v144
	v_exp_f32_e32 v145, v145
	v_fmamk_f32 v130, v130, 0x3c800000, v244
	v_fmamk_f32 v135, v135, 0x3c800000, v237
	v_fmamk_f32 v136, v136, 0x3c800000, v238
	v_fmamk_f32 v137, v137, 0x3c800000, v239
	v_fmamk_f32 v141, v141, 0x3c800000, v243
	v_exp_f32_e32 v139, v139
	v_exp_f32_e32 v140, v140
	v_fmamk_f32 v131, v131, 0x3c800000, v245
	v_fmamk_f32 v132, v132, 0x3c800000, v246
	v_med3_f32 v134, v134, s71, v172
	v_med3_f32 v130, v130, s71, v172
	v_med3_f32 v135, v135, s71, v172
	v_med3_f32 v136, v136, s71, v172
	v_med3_f32 v137, v137, s71, v172
	v_med3_f32 v141, v141, s71, v172
	v_fmamk_f32 v133, v133, 0x3c800000, v247
	v_med3_f32 v131, v131, s71, v172
	v_med3_f32 v132, v132, s71, v172
	v_mul_f32_e32 v134, 0xbfb8aa3b, v134
	v_mul_f32_e32 v159, 0xbfb8aa3b, v130
	v_mul_f32_e32 v135, 0xbfb8aa3b, v135
	v_mul_f32_e32 v136, 0xbfb8aa3b, v136
	v_mul_f32_e32 v137, 0xbfb8aa3b, v137
	v_mul_f32_e32 v141, 0xbfb8aa3b, v141
	v_med3_f32 v133, v133, s71, v172
	v_mul_f32_e32 v162, 0xbfb8aa3b, v131
	v_mul_f32_e32 v163, 0xbfb8aa3b, v132
	v_exp_f32_e32 v130, v134
	v_exp_f32_e32 v132, v159
	v_exp_f32_e32 v131, v135
	v_exp_f32_e32 v134, v136
	v_exp_f32_e32 v135, v137
	v_exp_f32_e32 v159, v141
	v_add_f32_e32 v141, 1.0, v142
	v_add_f32_e32 v142, 1.0, v138
	v_add_f32_e32 v143, 1.0, v143
	v_add_f32_e32 v144, 1.0, v144
	v_add_f32_e32 v145, 1.0, v145
	v_mul_f32_e32 v164, 0xbfb8aa3b, v133
	v_exp_f32_e32 v133, v162
	v_exp_f32_e32 v136, v163
	v_add_f32_e32 v162, 1.0, v139
	v_add_f32_e32 v163, 1.0, v140
	v_rcp_f32_e32 v138, v141
	v_rcp_f32_e32 v140, v142
	v_rcp_f32_e32 v139, v143
	v_rcp_f32_e32 v142, v144
	v_rcp_f32_e32 v143, v145
	v_pk_add_f32 v[130:131], v[130:131], 1.0 op_sel_hi:[1,0]
	v_pk_add_f32 v[134:135], v[134:135], 1.0 op_sel_hi:[1,0]
	v_exp_f32_e32 v137, v164
	v_rcp_f32_e32 v164, v130
	v_rcp_f32_e32 v165, v131
	v_rcp_f32_e32 v141, v162
	v_rcp_f32_e32 v144, v163
	v_pk_mul_f32 v[130:131], v[138:139], v[130:131]
	v_rcp_f32_e32 v163, v134
	v_pk_mul_f32 v[138:139], v[142:143], v[134:135]
	v_add_f32_e32 v134, 1.0, v159
	v_rcp_f32_e32 v145, v134
	v_pk_add_f32 v[132:133], v[132:133], 1.0 op_sel_hi:[1,0]
	v_rcp_f32_e32 v142, v135
	v_rcp_f32_e32 v162, v132
	v_rcp_f32_e32 v173, v133
	v_pk_mul_f32 v[132:133], v[140:141], v[132:133]
	v_pk_add_f32 v[134:135], v[136:137], 1.0 op_sel_hi:[1,0]
	v_ashrrev_i32_e32 v159, 31, v158
	v_rcp_f32_e32 v143, v134
	v_pk_mul_f32 v[140:141], v[144:145], v[134:135]
	v_rcp_f32_e32 v144, v135
	v_cvt_pk_bf16_f32 v136, v132, v133
	v_lshlrev_b64 v[132:133], 12, v[158:159]
	v_cvt_pk_bf16_f32 v134, v130, v131
	v_cvt_pk_bf16_f32 v135, v138, v139
	v_lshl_add_u64 v[138:139], s[4:5], 0, v[132:133]
	v_lshlrev_b64 v[130:131], 1, v[160:161]
	v_cvt_pk_bf16_f32 v137, v140, v141
	v_lshl_add_u64 v[138:139], v[138:139], 0, v[130:131]
	v_fmamk_f32 v126, v126, 0x3c800000, v232
	v_fmamk_f32 v122, v122, 0x3c800000, v240
	v_fmamk_f32 v127, v127, 0x3c800000, v233
	global_store_dwordx4 v[138:139], v[134:137], off
	v_lshl_add_u64 v[138:139], s[14:15], 0, v[132:133]
	v_med3_f32 v126, v126, s71, v172
	v_med3_f32 v122, v122, s71, v172
	v_med3_f32 v127, v127, s71, v172
	v_cvt_pk_bf16_f32 v134, v164, v165
	v_cvt_pk_bf16_f32 v135, v163, v142
	v_cvt_pk_bf16_f32 v136, v162, v173
	v_cvt_pk_bf16_f32 v137, v143, v144
	v_lshl_add_u64 v[138:139], v[138:139], 0, v[130:131]
	v_mul_f32_e32 v126, 0xbfb8aa3b, v126
	v_mul_f32_e32 v122, 0xbfb8aa3b, v122
	v_mul_f32_e32 v127, 0xbfb8aa3b, v127
	global_store_dwordx4 v[138:139], v[134:137], off
	v_exp_f32_e32 v126, v126
	v_exp_f32_e32 v127, v127
	v_exp_f32_e32 v134, v122
	v_fmamk_f32 v118, v118, 0x3c800000, v236
	v_fmamk_f32 v119, v119, 0x3c800000, v237
	v_fmamk_f32 v123, v123, 0x3c800000, v241
	v_med3_f32 v118, v118, s71, v172
	v_med3_f32 v119, v119, s71, v172
	v_med3_f32 v123, v123, s71, v172
	v_mul_f32_e32 v118, 0xbfb8aa3b, v118
	v_mul_f32_e32 v119, 0xbfb8aa3b, v119
	v_mul_f32_e32 v123, 0xbfb8aa3b, v123
	v_exp_f32_e32 v118, v118
	v_add_f32_e32 v122, 1.0, v126
	v_add_f32_e32 v126, 1.0, v134
	v_exp_f32_e32 v119, v119
	v_exp_f32_e32 v134, v123
	v_add_f32_e32 v123, 1.0, v127
	v_rcp_f32_e32 v122, v122
	v_rcp_f32_e32 v123, v123
	v_fmamk_f32 v114, v114, 0x3c800000, v244
	v_fmamk_f32 v115, v115, 0x3c800000, v245
	v_med3_f32 v114, v114, s71, v172
	v_med3_f32 v115, v115, s71, v172
	v_mul_f32_e32 v114, 0xbfb8aa3b, v114
	v_mul_f32_e32 v115, 0xbfb8aa3b, v115
	v_pk_add_f32 v[118:119], v[118:119], 1.0 op_sel_hi:[1,0]
; __device__ __forceinline__ unsigned pk_bf16(float lo, float hi) { const f32x2_t v = {lo, hi}; return __builtin_bit_cast(unsigned, __builtin_convertvector(v, bf16x2_t)); }
;     __device__ __forceinline__ bool operator()(f32x4 (&acc)[2][2][4][2], const Unit& u, int wr, int wc, int fr, int fq) const {
;     ...
;                 for (int m = 0; m < 4; ++m) { const int row = r0 + ai * HALF + m * 16;
;                     const f32x4 a0 = acc[ai][0][m][0] * gsc + ba0, a1 = acc[ai][0][m][1] * gsc + ba1, b0 = acc[ai][1][m][0] * gsc + bb0, b1 = acc[ai][1][m][1] * gsc + bb1;
;                     f32x4 r0v, r1v, s0v, s1v;
; #pragma unroll
;                     for (int j = 0; j < 4; ++j) {
;                         const float ea0 = __builtin_amdgcn_exp2f(-1.44269504f * fminf(fmaxf(a0[j], -40.f), 40.f)), eb0 = __builtin_amdgcn_exp2f(-1.44269504f * fminf(fmaxf(b0[j], -40.f), 40.f));
;                         const float ea1 = __builtin_amdgcn_exp2f(-1.44269504f * fminf(fmaxf(a1[j], -40.f), 40.f)), eb1 = __builtin_amdgcn_exp2f(-1.44269504f * fminf(fmaxf(b1[j], -40.f), 40.f));
;                         s0v[j] = __builtin_amdgcn_rcpf(1.0f + eb0); s1v[j] = __builtin_amdgcn_rcpf(1.0f + eb1);
;                         r0v[j] = (1.0f + eb0) * __builtin_amdgcn_rcpf(1.0f + ea0); r1v[j] = (1.0f + eb1) * __builtin_amdgcn_rcpf(1.0f + ea1); }
;                     u32x4 w; w.x = pk_bf16(r0v[0], r0v[1]); w.y = pk_bf16(r0v[2], r0v[3]); w.z = pk_bf16(r1v[0], r1v[1]); w.w = pk_bf16(r1v[2], r1v[3]);
;                     *(u32x4*)(SGR + (size_t)row * D + ch0) = w;
;                     w.x = pk_bf16(s0v[0], s0v[1]); w.y = pk_bf16(s0v[2], s0v[3]); w.z = pk_bf16(s1v[0], s1v[1]); w.w = pk_bf16(s1v[2], s1v[3]);
;                     *(u32x4*)(SGB + (size_t)row * D + ch0) = w; }
	v_exp_f32_e32 v114, v114
	v_exp_f32_e32 v115, v115
	v_rcp_f32_e32 v135, v118
	v_pk_mul_f32 v[122:123], v[122:123], v[118:119]
	v_add_f32_e32 v118, 1.0, v134
	v_rcp_f32_e32 v126, v126
	v_rcp_f32_e32 v127, v118
	v_pk_add_f32 v[114:115], v[114:115], 1.0 op_sel_hi:[1,0]
	v_rcp_f32_e32 v134, v119
	v_rcp_f32_e32 v136, v114
	v_pk_mul_f32 v[118:119], v[126:127], v[114:115]
	v_fmamk_f32 v114, v128, 0x3c800000, v234
	v_med3_f32 v114, v114, s71, v172
	v_mul_f32_e32 v114, 0xbfb8aa3b, v114
	v_rcp_f32_e32 v137, v115
	v_exp_f32_e32 v115, v114
	v_fmamk_f32 v114, v120, 0x3c800000, v238
	v_fmamk_f32 v120, v124, 0x3c800000, v242
	v_med3_f32 v120, v120, s71, v172
	v_mul_f32_e32 v120, 0xbfb8aa3b, v120
	v_exp_f32_e32 v124, v120
	v_add_f32_e32 v115, 1.0, v115
	v_rcp_f32_e32 v120, v115
	v_med3_f32 v114, v114, s71, v172
	v_add_f32_e32 v115, 1.0, v124
	v_rcp_f32_e32 v124, v115
	v_fmamk_f32 v115, v129, 0x3c800000, v235
	v_med3_f32 v115, v115, s71, v172
	v_mul_f32_e32 v115, 0xbfb8aa3b, v115
	v_exp_f32_e32 v126, v115
	v_fmamk_f32 v115, v121, 0x3c800000, v239
	v_fmamk_f32 v121, v125, 0x3c800000, v243
	v_med3_f32 v115, v115, s71, v172
	v_med3_f32 v121, v121, s71, v172
	v_mul_f32_e32 v114, 0xbfb8aa3b, v114
	v_mul_f32_e32 v115, 0xbfb8aa3b, v115
	v_mul_f32_e32 v121, 0xbfb8aa3b, v121
	v_exp_f32_e32 v114, v114
	v_fmamk_f32 v116, v116, 0x3c800000, v246
	v_exp_f32_e32 v115, v115
	v_exp_f32_e32 v125, v121
	v_fmamk_f32 v117, v117, 0x3c800000, v247
	v_add_f32_e32 v121, 1.0, v126
	v_med3_f32 v116, v116, s71, v172
	v_med3_f32 v117, v117, s71, v172
	v_rcp_f32_e32 v121, v121
	v_mul_f32_e32 v116, 0xbfb8aa3b, v116
	v_mul_f32_e32 v117, 0xbfb8aa3b, v117
	v_exp_f32_e32 v116, v116
	v_exp_f32_e32 v117, v117
	v_pk_add_f32 v[114:115], v[114:115], 1.0 op_sel_hi:[1,0]
	v_or_b32_e32 v126, 16, v158
	v_rcp_f32_e32 v128, v114
	v_pk_mul_f32 v[120:121], v[120:121], v[114:115]
	v_add_f32_e32 v114, 1.0, v125
	v_rcp_f32_e32 v125, v114
	v_rcp_f32_e32 v129, v115
	v_pk_add_f32 v[114:115], v[116:117], 1.0 op_sel_hi:[1,0]
	v_ashrrev_i32_e32 v127, 31, v126
	v_rcp_f32_e32 v138, v114
	v_rcp_f32_e32 v139, v115
	v_cvt_pk_bf16_f32 v116, v118, v119
	v_lshlrev_b64 v[118:119], 12, v[126:127]
	v_pk_mul_f32 v[124:125], v[124:125], v[114:115]
	v_cvt_pk_bf16_f32 v115, v120, v121
	v_lshl_add_u64 v[120:121], s[4:5], 0, v[118:119]
	v_fmamk_f32 v110, v110, 0x3c800000, v232
	v_fmamk_f32 v106, v106, 0x3c800000, v240
	v_fmamk_f32 v111, v111, 0x3c800000, v233
	v_cvt_pk_bf16_f32 v114, v122, v123
	v_cvt_pk_bf16_f32 v117, v124, v125
	v_lshl_add_u64 v[120:121], v[120:121], 0, v[130:131]
	v_lshl_add_u64 v[118:119], s[14:15], 0, v[118:119]
	v_med3_f32 v110, v110, s71, v172
	v_med3_f32 v106, v106, s71, v172
	v_med3_f32 v111, v111, s71, v172
	global_store_dwordx4 v[120:121], v[114:117], off
	v_lshl_add_u64 v[118:119], v[118:119], 0, v[130:131]
	v_mul_f32_e32 v110, 0xbfb8aa3b, v110
	v_cvt_pk_bf16_f32 v114, v135, v134
	v_cvt_pk_bf16_f32 v115, v128, v129
	v_cvt_pk_bf16_f32 v116, v136, v137
	v_cvt_pk_bf16_f32 v117, v138, v139
	v_mul_f32_e32 v106, 0xbfb8aa3b, v106
	v_mul_f32_e32 v111, 0xbfb8aa3b, v111
	global_store_dwordx4 v[118:119], v[114:117], off
	v_exp_f32_e32 v110, v110
	v_exp_f32_e32 v111, v111
	v_exp_f32_e32 v114, v106
	v_fmamk_f32 v102, v102, 0x3c800000, v236
	v_fmamk_f32 v103, v103, 0x3c800000, v237
	v_fmamk_f32 v107, v107, 0x3c800000, v241
	v_med3_f32 v102, v102, s71, v172
	v_med3_f32 v103, v103, s71, v172
	v_med3_f32 v107, v107, s71, v172
	v_mul_f32_e32 v102, 0xbfb8aa3b, v102
	v_mul_f32_e32 v103, 0xbfb8aa3b, v103
	v_mul_f32_e32 v107, 0xbfb8aa3b, v107
	v_exp_f32_e32 v102, v102
	v_add_f32_e32 v106, 1.0, v110
	v_add_f32_e32 v110, 1.0, v114
	v_exp_f32_e32 v103, v103
	v_exp_f32_e32 v114, v107
	v_add_f32_e32 v107, 1.0, v111
	v_rcp_f32_e32 v106, v106
	v_rcp_f32_e32 v107, v107
	v_fmamk_f32 v98, v98, 0x3c800000, v244
	v_fmamk_f32 v99, v99, 0x3c800000, v245
	v_med3_f32 v98, v98, s71, v172
	v_med3_f32 v99, v99, s71, v172
	v_mul_f32_e32 v98, 0xbfb8aa3b, v98
	v_mul_f32_e32 v99, 0xbfb8aa3b, v99
	v_pk_add_f32 v[102:103], v[102:103], 1.0 op_sel_hi:[1,0]
	v_exp_f32_e32 v98, v98
	v_exp_f32_e32 v99, v99
	v_rcp_f32_e32 v115, v102
	v_pk_mul_f32 v[106:107], v[106:107], v[102:103]
	v_add_f32_e32 v102, 1.0, v114
	v_rcp_f32_e32 v110, v110
	v_rcp_f32_e32 v111, v102
	v_pk_add_f32 v[98:99], v[98:99], 1.0 op_sel_hi:[1,0]
	v_rcp_f32_e32 v114, v103
	v_rcp_f32_e32 v116, v98
	v_pk_mul_f32 v[102:103], v[110:111], v[98:99]
	v_fmamk_f32 v98, v112, 0x3c800000, v234
	v_med3_f32 v98, v98, s71, v172
	v_mul_f32_e32 v98, 0xbfb8aa3b, v98
	v_rcp_f32_e32 v117, v99
	v_exp_f32_e32 v99, v98
	v_fmamk_f32 v98, v104, 0x3c800000, v238
	v_fmamk_f32 v104, v108, 0x3c800000, v242
	v_med3_f32 v104, v104, s71, v172
	v_mul_f32_e32 v104, 0xbfb8aa3b, v104
	v_exp_f32_e32 v108, v104
	v_add_f32_e32 v99, 1.0, v99
	v_rcp_f32_e32 v104, v99
	v_med3_f32 v98, v98, s71, v172
	v_add_f32_e32 v99, 1.0, v108
	v_rcp_f32_e32 v108, v99
	v_fmamk_f32 v99, v113, 0x3c800000, v235
	v_med3_f32 v99, v99, s71, v172
	v_mul_f32_e32 v99, 0xbfb8aa3b, v99
	v_exp_f32_e32 v110, v99
	v_fmamk_f32 v99, v105, 0x3c800000, v239
	v_fmamk_f32 v105, v109, 0x3c800000, v243
	v_med3_f32 v99, v99, s71, v172
	v_med3_f32 v105, v105, s71, v172
	v_mul_f32_e32 v98, 0xbfb8aa3b, v98
	v_mul_f32_e32 v99, 0xbfb8aa3b, v99
	v_mul_f32_e32 v105, 0xbfb8aa3b, v105
	v_exp_f32_e32 v98, v98
	v_fmamk_f32 v100, v100, 0x3c800000, v246
	v_exp_f32_e32 v99, v99
	v_exp_f32_e32 v109, v105
	v_fmamk_f32 v101, v101, 0x3c800000, v247
	v_add_f32_e32 v105, 1.0, v110
	v_med3_f32 v100, v100, s71, v172
	v_med3_f32 v101, v101, s71, v172
	v_rcp_f32_e32 v105, v105
	v_mul_f32_e32 v100, 0xbfb8aa3b, v100
	v_mul_f32_e32 v101, 0xbfb8aa3b, v101
	v_exp_f32_e32 v100, v100
; __device__ __forceinline__ unsigned pk_bf16(float lo, float hi) { const f32x2_t v = {lo, hi}; return __builtin_bit_cast(unsigned, __builtin_convertvector(v, bf16x2_t)); }
;     __device__ __forceinline__ bool operator()(f32x4 (&acc)[2][2][4][2], const Unit& u, int wr, int wc, int fr, int fq) const {
;     ...
;                 for (int m = 0; m < 4; ++m) { const int row = r0 + ai * HALF + m * 16;
;                     const f32x4 a0 = acc[ai][0][m][0] * gsc + ba0, a1 = acc[ai][0][m][1] * gsc + ba1, b0 = acc[ai][1][m][0] * gsc + bb0, b1 = acc[ai][1][m][1] * gsc + bb1;
;                     f32x4 r0v, r1v, s0v, s1v;
; #pragma unroll
;                     for (int j = 0; j < 4; ++j) {
;                         const float ea0 = __builtin_amdgcn_exp2f(-1.44269504f * fminf(fmaxf(a0[j], -40.f), 40.f)), eb0 = __builtin_amdgcn_exp2f(-1.44269504f * fminf(fmaxf(b0[j], -40.f), 40.f));
;                         const float ea1 = __builtin_amdgcn_exp2f(-1.44269504f * fminf(fmaxf(a1[j], -40.f), 40.f)), eb1 = __builtin_amdgcn_exp2f(-1.44269504f * fminf(fmaxf(b1[j], -40.f), 40.f));
;                         s0v[j] = __builtin_amdgcn_rcpf(1.0f + eb0); s1v[j] = __builtin_amdgcn_rcpf(1.0f + eb1);
;                         r0v[j] = (1.0f + eb0) * __builtin_amdgcn_rcpf(1.0f + ea0); r1v[j] = (1.0f + eb1) * __builtin_amdgcn_rcpf(1.0f + ea1); }
;                     u32x4 w; w.x = pk_bf16(r0v[0], r0v[1]); w.y = pk_bf16(r0v[2], r0v[3]); w.z = pk_bf16(r1v[0], r1v[1]); w.w = pk_bf16(r1v[2], r1v[3]);
;                     *(u32x4*)(SGR + (size_t)row * D + ch0) = w;
;                     w.x = pk_bf16(s0v[0], s0v[1]); w.y = pk_bf16(s0v[2], s0v[3]); w.z = pk_bf16(s1v[0], s1v[1]); w.w = pk_bf16(s1v[2], s1v[3]);
;                     *(u32x4*)(SGB + (size_t)row * D + ch0) = w; }
	v_exp_f32_e32 v101, v101
	v_pk_add_f32 v[98:99], v[98:99], 1.0 op_sel_hi:[1,0]
	v_or_b32_e32 v110, 32, v158
	v_rcp_f32_e32 v112, v98
	v_pk_mul_f32 v[104:105], v[104:105], v[98:99]
	v_add_f32_e32 v98, 1.0, v109
	v_rcp_f32_e32 v109, v98
	v_rcp_f32_e32 v113, v99
	v_pk_add_f32 v[98:99], v[100:101], 1.0 op_sel_hi:[1,0]
	v_ashrrev_i32_e32 v111, 31, v110
	v_rcp_f32_e32 v118, v98
	v_rcp_f32_e32 v119, v99
	v_cvt_pk_bf16_f32 v100, v102, v103
	v_lshlrev_b64 v[102:103], 12, v[110:111]
	v_pk_mul_f32 v[108:109], v[108:109], v[98:99]
	v_cvt_pk_bf16_f32 v99, v104, v105
	v_lshl_add_u64 v[104:105], s[4:5], 0, v[102:103]
	v_fmamk_f32 v94, v94, 0x3c800000, v232
	v_fmamk_f32 v90, v90, 0x3c800000, v240
	v_fmamk_f32 v95, v95, 0x3c800000, v233
	v_cvt_pk_bf16_f32 v98, v106, v107
	v_cvt_pk_bf16_f32 v101, v108, v109
	v_lshl_add_u64 v[104:105], v[104:105], 0, v[130:131]
	v_lshl_add_u64 v[102:103], s[14:15], 0, v[102:103]
	v_med3_f32 v94, v94, s71, v172
	v_med3_f32 v90, v90, s71, v172
	v_med3_f32 v95, v95, s71, v172
	global_store_dwordx4 v[104:105], v[98:101], off
	v_lshl_add_u64 v[102:103], v[102:103], 0, v[130:131]
	v_mul_f32_e32 v94, 0xbfb8aa3b, v94
	v_cvt_pk_bf16_f32 v98, v115, v114
	v_cvt_pk_bf16_f32 v99, v112, v113
	v_cvt_pk_bf16_f32 v100, v116, v117
	v_cvt_pk_bf16_f32 v101, v118, v119
	v_mul_f32_e32 v90, 0xbfb8aa3b, v90
	v_mul_f32_e32 v95, 0xbfb8aa3b, v95
	global_store_dwordx4 v[102:103], v[98:101], off
	v_exp_f32_e32 v94, v94
	v_exp_f32_e32 v95, v95
	v_exp_f32_e32 v98, v90
	v_fmamk_f32 v86, v86, 0x3c800000, v236
	v_fmamk_f32 v87, v87, 0x3c800000, v237
	v_fmamk_f32 v91, v91, 0x3c800000, v241
	v_med3_f32 v86, v86, s71, v172
	v_med3_f32 v87, v87, s71, v172
	v_med3_f32 v91, v91, s71, v172
	v_mul_f32_e32 v86, 0xbfb8aa3b, v86
	v_mul_f32_e32 v87, 0xbfb8aa3b, v87
	v_mul_f32_e32 v91, 0xbfb8aa3b, v91
	v_exp_f32_e32 v86, v86
	v_add_f32_e32 v90, 1.0, v94
	v_add_f32_e32 v94, 1.0, v98
	v_exp_f32_e32 v87, v87
	v_exp_f32_e32 v98, v91
	v_add_f32_e32 v91, 1.0, v95
	v_rcp_f32_e32 v90, v90
	v_rcp_f32_e32 v91, v91
	v_fmamk_f32 v82, v82, 0x3c800000, v244
	v_fmamk_f32 v83, v83, 0x3c800000, v245
	v_med3_f32 v82, v82, s71, v172
	v_med3_f32 v83, v83, s71, v172
	v_mul_f32_e32 v82, 0xbfb8aa3b, v82
	v_mul_f32_e32 v83, 0xbfb8aa3b, v83
	v_pk_add_f32 v[86:87], v[86:87], 1.0 op_sel_hi:[1,0]
	v_exp_f32_e32 v82, v82
	v_exp_f32_e32 v83, v83
	v_rcp_f32_e32 v99, v86
	v_pk_mul_f32 v[90:91], v[90:91], v[86:87]
	v_add_f32_e32 v86, 1.0, v98
	v_rcp_f32_e32 v94, v94
	v_rcp_f32_e32 v95, v86
	v_pk_add_f32 v[82:83], v[82:83], 1.0 op_sel_hi:[1,0]
	v_rcp_f32_e32 v98, v87
	v_rcp_f32_e32 v100, v82
	v_pk_mul_f32 v[86:87], v[94:95], v[82:83]
	v_fmamk_f32 v82, v96, 0x3c800000, v234
	v_med3_f32 v82, v82, s71, v172
	v_mul_f32_e32 v82, 0xbfb8aa3b, v82
	v_rcp_f32_e32 v101, v83
	v_exp_f32_e32 v83, v82
	v_fmamk_f32 v82, v88, 0x3c800000, v238
	v_fmamk_f32 v88, v92, 0x3c800000, v242
	v_med3_f32 v88, v88, s71, v172
	v_mul_f32_e32 v88, 0xbfb8aa3b, v88
	v_exp_f32_e32 v92, v88
	v_add_f32_e32 v83, 1.0, v83
	v_rcp_f32_e32 v88, v83
	v_med3_f32 v82, v82, s71, v172
	v_add_f32_e32 v83, 1.0, v92
	v_rcp_f32_e32 v92, v83
	v_fmamk_f32 v83, v97, 0x3c800000, v235
	v_med3_f32 v83, v83, s71, v172
	v_mul_f32_e32 v83, 0xbfb8aa3b, v83
	v_exp_f32_e32 v94, v83
	v_fmamk_f32 v83, v89, 0x3c800000, v239
	v_fmamk_f32 v89, v93, 0x3c800000, v243
	v_med3_f32 v83, v83, s71, v172
	v_med3_f32 v89, v89, s71, v172
	v_mul_f32_e32 v82, 0xbfb8aa3b, v82
	v_mul_f32_e32 v83, 0xbfb8aa3b, v83
	v_mul_f32_e32 v89, 0xbfb8aa3b, v89
	v_exp_f32_e32 v82, v82
	v_fmamk_f32 v84, v84, 0x3c800000, v246
	v_exp_f32_e32 v83, v83
	v_exp_f32_e32 v93, v89
	v_fmamk_f32 v85, v85, 0x3c800000, v247
	v_add_f32_e32 v89, 1.0, v94
	v_med3_f32 v84, v84, s71, v172
	v_med3_f32 v85, v85, s71, v172
	v_rcp_f32_e32 v89, v89
	v_mul_f32_e32 v84, 0xbfb8aa3b, v84
	v_mul_f32_e32 v85, 0xbfb8aa3b, v85
	v_exp_f32_e32 v84, v84
	v_exp_f32_e32 v85, v85
	v_pk_add_f32 v[82:83], v[82:83], 1.0 op_sel_hi:[1,0]
	v_or_b32_e32 v94, 48, v158
	v_rcp_f32_e32 v96, v82
	v_pk_mul_f32 v[88:89], v[88:89], v[82:83]
	v_add_f32_e32 v82, 1.0, v93
	v_rcp_f32_e32 v93, v82
	v_rcp_f32_e32 v97, v83
	v_pk_add_f32 v[82:83], v[84:85], 1.0 op_sel_hi:[1,0]
	v_ashrrev_i32_e32 v95, 31, v94
	v_rcp_f32_e32 v102, v82
	v_rcp_f32_e32 v103, v83
	v_cvt_pk_bf16_f32 v84, v86, v87
	v_lshlrev_b64 v[86:87], 12, v[94:95]
	v_pk_mul_f32 v[92:93], v[92:93], v[82:83]
	v_cvt_pk_bf16_f32 v83, v88, v89
	v_lshl_add_u64 v[88:89], s[4:5], 0, v[86:87]
	v_fmamk_f32 v78, v78, 0x3c800000, v232
	v_fmamk_f32 v74, v74, 0x3c800000, v240
	v_fmamk_f32 v79, v79, 0x3c800000, v233
	v_cvt_pk_bf16_f32 v82, v90, v91
	v_cvt_pk_bf16_f32 v85, v92, v93
	v_lshl_add_u64 v[88:89], v[88:89], 0, v[130:131]
	v_lshl_add_u64 v[86:87], s[14:15], 0, v[86:87]
	v_med3_f32 v78, v78, s71, v172
	v_med3_f32 v74, v74, s71, v172
	v_med3_f32 v79, v79, s71, v172
	global_store_dwordx4 v[88:89], v[82:85], off
	v_lshl_add_u64 v[86:87], v[86:87], 0, v[130:131]
	v_mul_f32_e32 v78, 0xbfb8aa3b, v78
	v_cvt_pk_bf16_f32 v82, v99, v98
	v_cvt_pk_bf16_f32 v83, v96, v97
	v_cvt_pk_bf16_f32 v84, v100, v101
	v_cvt_pk_bf16_f32 v85, v102, v103
	v_mul_f32_e32 v74, 0xbfb8aa3b, v74
	v_mul_f32_e32 v79, 0xbfb8aa3b, v79
	global_store_dwordx4 v[86:87], v[82:85], off
	v_exp_f32_e32 v78, v78
	v_exp_f32_e32 v79, v79
	v_exp_f32_e32 v82, v74
	v_fmamk_f32 v70, v70, 0x3c800000, v236
	v_fmamk_f32 v71, v71, 0x3c800000, v237
	v_fmamk_f32 v75, v75, 0x3c800000, v241
	v_med3_f32 v70, v70, s71, v172
	v_med3_f32 v71, v71, s71, v172
	v_med3_f32 v75, v75, s71, v172
	v_mul_f32_e32 v70, 0xbfb8aa3b, v70
	v_mul_f32_e32 v71, 0xbfb8aa3b, v71
	v_mul_f32_e32 v75, 0xbfb8aa3b, v75
	v_exp_f32_e32 v70, v70
	v_add_f32_e32 v74, 1.0, v78
; __device__ __forceinline__ unsigned pk_bf16(float lo, float hi) { const f32x2_t v = {lo, hi}; return __builtin_bit_cast(unsigned, __builtin_convertvector(v, bf16x2_t)); }
;     __device__ __forceinline__ bool operator()(f32x4 (&acc)[2][2][4][2], const Unit& u, int wr, int wc, int fr, int fq) const {
;     ...
;                 for (int m = 0; m < 4; ++m) { const int row = r0 + ai * HALF + m * 16;
;                     const f32x4 a0 = acc[ai][0][m][0] * gsc + ba0, a1 = acc[ai][0][m][1] * gsc + ba1, b0 = acc[ai][1][m][0] * gsc + bb0, b1 = acc[ai][1][m][1] * gsc + bb1;
;                     f32x4 r0v, r1v, s0v, s1v;
; #pragma unroll
;                     for (int j = 0; j < 4; ++j) {
;                         const float ea0 = __builtin_amdgcn_exp2f(-1.44269504f * fminf(fmaxf(a0[j], -40.f), 40.f)), eb0 = __builtin_amdgcn_exp2f(-1.44269504f * fminf(fmaxf(b0[j], -40.f), 40.f));
;                         const float ea1 = __builtin_amdgcn_exp2f(-1.44269504f * fminf(fmaxf(a1[j], -40.f), 40.f)), eb1 = __builtin_amdgcn_exp2f(-1.44269504f * fminf(fmaxf(b1[j], -40.f), 40.f));
;                         s0v[j] = __builtin_amdgcn_rcpf(1.0f + eb0); s1v[j] = __builtin_amdgcn_rcpf(1.0f + eb1);
;                         r0v[j] = (1.0f + eb0) * __builtin_amdgcn_rcpf(1.0f + ea0); r1v[j] = (1.0f + eb1) * __builtin_amdgcn_rcpf(1.0f + ea1); }
;                     u32x4 w; w.x = pk_bf16(r0v[0], r0v[1]); w.y = pk_bf16(r0v[2], r0v[3]); w.z = pk_bf16(r1v[0], r1v[1]); w.w = pk_bf16(r1v[2], r1v[3]);
;                     *(u32x4*)(SGR + (size_t)row * D + ch0) = w;
;                     w.x = pk_bf16(s0v[0], s0v[1]); w.y = pk_bf16(s0v[2], s0v[3]); w.z = pk_bf16(s1v[0], s1v[1]); w.w = pk_bf16(s1v[2], s1v[3]);
;                     *(u32x4*)(SGB + (size_t)row * D + ch0) = w; }
	v_add_f32_e32 v78, 1.0, v82
	v_exp_f32_e32 v71, v71
	v_exp_f32_e32 v82, v75
	v_add_f32_e32 v75, 1.0, v79
	v_rcp_f32_e32 v74, v74
	v_rcp_f32_e32 v75, v75
	v_fmamk_f32 v66, v66, 0x3c800000, v244
	v_fmamk_f32 v67, v67, 0x3c800000, v245
	v_med3_f32 v66, v66, s71, v172
	v_med3_f32 v67, v67, s71, v172
	v_mul_f32_e32 v66, 0xbfb8aa3b, v66
	v_mul_f32_e32 v67, 0xbfb8aa3b, v67
	v_pk_add_f32 v[70:71], v[70:71], 1.0 op_sel_hi:[1,0]
	v_exp_f32_e32 v66, v66
	v_exp_f32_e32 v67, v67
	v_rcp_f32_e32 v83, v70
	v_pk_mul_f32 v[74:75], v[74:75], v[70:71]
	v_add_f32_e32 v70, 1.0, v82
	v_rcp_f32_e32 v78, v78
	v_rcp_f32_e32 v79, v70
	v_pk_add_f32 v[66:67], v[66:67], 1.0 op_sel_hi:[1,0]
	v_rcp_f32_e32 v82, v71
	v_rcp_f32_e32 v84, v66
	v_pk_mul_f32 v[70:71], v[78:79], v[66:67]
	v_fmamk_f32 v66, v80, 0x3c800000, v234
	v_med3_f32 v66, v66, s71, v172
	v_mul_f32_e32 v66, 0xbfb8aa3b, v66
	v_rcp_f32_e32 v78, v67
	v_exp_f32_e32 v67, v66
	v_fmamk_f32 v66, v72, 0x3c800000, v238
	v_fmamk_f32 v72, v76, 0x3c800000, v242
	v_med3_f32 v72, v72, s71, v172
	v_mul_f32_e32 v72, 0xbfb8aa3b, v72
	v_exp_f32_e32 v76, v72
	v_add_f32_e32 v67, 1.0, v67
	v_rcp_f32_e32 v72, v67
	v_med3_f32 v66, v66, s71, v172
	v_add_f32_e32 v67, 1.0, v76
	v_rcp_f32_e32 v76, v67
	v_fmamk_f32 v67, v81, 0x3c800000, v235
	v_med3_f32 v67, v67, s71, v172
	v_mul_f32_e32 v67, 0xbfb8aa3b, v67
	v_exp_f32_e32 v79, v67
	v_fmamk_f32 v67, v73, 0x3c800000, v239
	v_fmamk_f32 v73, v77, 0x3c800000, v243
	v_med3_f32 v67, v67, s71, v172
	v_med3_f32 v73, v73, s71, v172
	v_mul_f32_e32 v66, 0xbfb8aa3b, v66
	v_mul_f32_e32 v67, 0xbfb8aa3b, v67
	v_mul_f32_e32 v73, 0xbfb8aa3b, v73
	v_exp_f32_e32 v66, v66
	v_fmamk_f32 v68, v68, 0x3c800000, v246
	v_exp_f32_e32 v67, v67
	v_exp_f32_e32 v77, v73
	v_fmamk_f32 v69, v69, 0x3c800000, v247
	v_add_f32_e32 v73, 1.0, v79
	v_med3_f32 v68, v68, s71, v172
	v_med3_f32 v69, v69, s71, v172
	v_rcp_f32_e32 v73, v73
	v_mul_f32_e32 v68, 0xbfb8aa3b, v68
	v_mul_f32_e32 v69, 0xbfb8aa3b, v69
	v_exp_f32_e32 v68, v68
	v_exp_f32_e32 v69, v69
	v_pk_add_f32 v[66:67], v[66:67], 1.0 op_sel_hi:[1,0]
	v_fmamk_f32 v62, v62, 0x3c800000, v232
	v_rcp_f32_e32 v79, v66
	v_pk_mul_f32 v[72:73], v[72:73], v[66:67]
	v_add_f32_e32 v66, 1.0, v77
	v_rcp_f32_e32 v77, v66
	v_rcp_f32_e32 v80, v67
	v_pk_add_f32 v[66:67], v[68:69], 1.0 op_sel_hi:[1,0]
	v_cvt_pk_bf16_f32 v68, v70, v71
	v_rcp_f32_e32 v81, v66
	v_rcp_f32_e32 v85, v67
	v_lshl_add_u64 v[70:71], v[132:133], 0, s[18:19]
	v_pk_mul_f32 v[76:77], v[76:77], v[66:67]
	v_cvt_pk_bf16_f32 v67, v72, v73
	v_lshl_add_u64 v[72:73], s[4:5], 0, v[70:71]
	v_fmamk_f32 v58, v58, 0x3c800000, v240
	v_fmamk_f32 v63, v63, 0x3c800000, v233
	v_cvt_pk_bf16_f32 v66, v74, v75
	v_cvt_pk_bf16_f32 v69, v76, v77
	v_lshl_add_u64 v[72:73], v[72:73], 0, v[130:131]
	v_lshl_add_u64 v[70:71], s[14:15], 0, v[70:71]
	v_med3_f32 v62, v62, s71, v172
	v_med3_f32 v58, v58, s71, v172
	v_med3_f32 v63, v63, s71, v172
	global_store_dwordx4 v[72:73], v[66:69], off
	v_lshl_add_u64 v[70:71], v[70:71], 0, v[130:131]
	v_mul_f32_e32 v62, 0xbfb8aa3b, v62
	v_cvt_pk_bf16_f32 v66, v83, v82
	v_cvt_pk_bf16_f32 v67, v79, v80
	v_cvt_pk_bf16_f32 v68, v84, v78
	v_cvt_pk_bf16_f32 v69, v81, v85
	v_mul_f32_e32 v58, 0xbfb8aa3b, v58
	v_mul_f32_e32 v63, 0xbfb8aa3b, v63
	global_store_dwordx4 v[70:71], v[66:69], off
	v_exp_f32_e32 v62, v62
	v_exp_f32_e32 v63, v63
	v_exp_f32_e32 v66, v58
	v_fmamk_f32 v54, v54, 0x3c800000, v236
	v_fmamk_f32 v55, v55, 0x3c800000, v237
	v_fmamk_f32 v59, v59, 0x3c800000, v241
	v_med3_f32 v54, v54, s71, v172
	v_med3_f32 v55, v55, s71, v172
	v_med3_f32 v59, v59, s71, v172
	v_mul_f32_e32 v54, 0xbfb8aa3b, v54
	v_mul_f32_e32 v55, 0xbfb8aa3b, v55
	v_mul_f32_e32 v59, 0xbfb8aa3b, v59
	v_exp_f32_e32 v54, v54
	v_add_f32_e32 v58, 1.0, v62
	v_add_f32_e32 v62, 1.0, v66
	v_exp_f32_e32 v55, v55
	v_exp_f32_e32 v66, v59
	v_add_f32_e32 v59, 1.0, v63
	v_rcp_f32_e32 v58, v58
	v_rcp_f32_e32 v59, v59
	v_fmamk_f32 v50, v50, 0x3c800000, v244
	v_fmamk_f32 v51, v51, 0x3c800000, v245
	v_med3_f32 v50, v50, s71, v172
	v_med3_f32 v51, v51, s71, v172
	v_mul_f32_e32 v50, 0xbfb8aa3b, v50
	v_mul_f32_e32 v51, 0xbfb8aa3b, v51
	v_pk_add_f32 v[54:55], v[54:55], 1.0 op_sel_hi:[1,0]
	v_exp_f32_e32 v50, v50
	v_exp_f32_e32 v51, v51
	v_rcp_f32_e32 v67, v54
	v_pk_mul_f32 v[58:59], v[58:59], v[54:55]
	v_add_f32_e32 v54, 1.0, v66
	v_rcp_f32_e32 v62, v62
	v_rcp_f32_e32 v63, v54
	v_pk_add_f32 v[50:51], v[50:51], 1.0 op_sel_hi:[1,0]
	v_rcp_f32_e32 v66, v55
	v_rcp_f32_e32 v68, v50
	v_pk_mul_f32 v[54:55], v[62:63], v[50:51]
	v_fmamk_f32 v50, v64, 0x3c800000, v234
	v_med3_f32 v50, v50, s71, v172
	v_mul_f32_e32 v50, 0xbfb8aa3b, v50
	v_rcp_f32_e32 v62, v51
	v_exp_f32_e32 v51, v50
	v_fmamk_f32 v50, v56, 0x3c800000, v238
	v_fmamk_f32 v56, v60, 0x3c800000, v242
	v_med3_f32 v56, v56, s71, v172
	v_mul_f32_e32 v56, 0xbfb8aa3b, v56
	v_exp_f32_e32 v60, v56
	v_add_f32_e32 v51, 1.0, v51
	v_rcp_f32_e32 v56, v51
	v_med3_f32 v50, v50, s71, v172
	v_add_f32_e32 v51, 1.0, v60
	v_rcp_f32_e32 v60, v51
	v_fmamk_f32 v51, v65, 0x3c800000, v235
	v_med3_f32 v51, v51, s71, v172
	v_mul_f32_e32 v51, 0xbfb8aa3b, v51
	v_exp_f32_e32 v63, v51
	v_fmamk_f32 v51, v57, 0x3c800000, v239
	v_fmamk_f32 v57, v61, 0x3c800000, v243
	v_med3_f32 v51, v51, s71, v172
	v_med3_f32 v57, v57, s71, v172
	v_mul_f32_e32 v50, 0xbfb8aa3b, v50
	v_mul_f32_e32 v51, 0xbfb8aa3b, v51
	v_mul_f32_e32 v57, 0xbfb8aa3b, v57
	v_exp_f32_e32 v50, v50
	v_fmamk_f32 v52, v52, 0x3c800000, v246
	v_exp_f32_e32 v51, v51
	v_exp_f32_e32 v61, v57
	v_fmamk_f32 v53, v53, 0x3c800000, v247
	v_add_f32_e32 v57, 1.0, v63
	v_med3_f32 v52, v52, s71, v172
	v_med3_f32 v53, v53, s71, v172
	v_rcp_f32_e32 v57, v57
	v_mul_f32_e32 v52, 0xbfb8aa3b, v52
; __device__ __forceinline__ unsigned pk_bf16(float lo, float hi) { const f32x2_t v = {lo, hi}; return __builtin_bit_cast(unsigned, __builtin_convertvector(v, bf16x2_t)); }
;     __device__ __forceinline__ bool operator()(f32x4 (&acc)[2][2][4][2], const Unit& u, int wr, int wc, int fr, int fq) const {
;     ...
;                 for (int m = 0; m < 4; ++m) { const int row = r0 + ai * HALF + m * 16;
;                     const f32x4 a0 = acc[ai][0][m][0] * gsc + ba0, a1 = acc[ai][0][m][1] * gsc + ba1, b0 = acc[ai][1][m][0] * gsc + bb0, b1 = acc[ai][1][m][1] * gsc + bb1;
;                     f32x4 r0v, r1v, s0v, s1v;
; #pragma unroll
;                     for (int j = 0; j < 4; ++j) {
;                         const float ea0 = __builtin_amdgcn_exp2f(-1.44269504f * fminf(fmaxf(a0[j], -40.f), 40.f)), eb0 = __builtin_amdgcn_exp2f(-1.44269504f * fminf(fmaxf(b0[j], -40.f), 40.f));
;                         const float ea1 = __builtin_amdgcn_exp2f(-1.44269504f * fminf(fmaxf(a1[j], -40.f), 40.f)), eb1 = __builtin_amdgcn_exp2f(-1.44269504f * fminf(fmaxf(b1[j], -40.f), 40.f));
;                         s0v[j] = __builtin_amdgcn_rcpf(1.0f + eb0); s1v[j] = __builtin_amdgcn_rcpf(1.0f + eb1);
;                         r0v[j] = (1.0f + eb0) * __builtin_amdgcn_rcpf(1.0f + ea0); r1v[j] = (1.0f + eb1) * __builtin_amdgcn_rcpf(1.0f + ea1); }
;                     u32x4 w; w.x = pk_bf16(r0v[0], r0v[1]); w.y = pk_bf16(r0v[2], r0v[3]); w.z = pk_bf16(r1v[0], r1v[1]); w.w = pk_bf16(r1v[2], r1v[3]);
;                     *(u32x4*)(SGR + (size_t)row * D + ch0) = w;
;                     w.x = pk_bf16(s0v[0], s0v[1]); w.y = pk_bf16(s0v[2], s0v[3]); w.z = pk_bf16(s1v[0], s1v[1]); w.w = pk_bf16(s1v[2], s1v[3]);
;                     *(u32x4*)(SGB + (size_t)row * D + ch0) = w; }
	v_mul_f32_e32 v53, 0xbfb8aa3b, v53
	v_exp_f32_e32 v52, v52
	v_exp_f32_e32 v53, v53
	v_pk_add_f32 v[50:51], v[50:51], 1.0 op_sel_hi:[1,0]
	v_fmamk_f32 v46, v46, 0x3c800000, v232
	v_rcp_f32_e32 v63, v50
	v_pk_mul_f32 v[56:57], v[56:57], v[50:51]
	v_add_f32_e32 v50, 1.0, v61
	v_rcp_f32_e32 v61, v50
	v_rcp_f32_e32 v64, v51
	v_pk_add_f32 v[50:51], v[52:53], 1.0 op_sel_hi:[1,0]
	v_cvt_pk_bf16_f32 v52, v54, v55
	v_rcp_f32_e32 v65, v50
	v_rcp_f32_e32 v69, v51
	v_lshl_add_u64 v[54:55], v[132:133], 0, s[20:21]
	v_pk_mul_f32 v[60:61], v[60:61], v[50:51]
	v_cvt_pk_bf16_f32 v51, v56, v57
	v_lshl_add_u64 v[56:57], s[4:5], 0, v[54:55]
	v_fmamk_f32 v42, v42, 0x3c800000, v240
	v_fmamk_f32 v47, v47, 0x3c800000, v233
	v_cvt_pk_bf16_f32 v50, v58, v59
	v_cvt_pk_bf16_f32 v53, v60, v61
	v_lshl_add_u64 v[56:57], v[56:57], 0, v[130:131]
	v_lshl_add_u64 v[54:55], s[14:15], 0, v[54:55]
	v_med3_f32 v46, v46, s71, v172
	v_med3_f32 v42, v42, s71, v172
	v_med3_f32 v47, v47, s71, v172
	global_store_dwordx4 v[56:57], v[50:53], off
	v_lshl_add_u64 v[54:55], v[54:55], 0, v[130:131]
	v_mul_f32_e32 v46, 0xbfb8aa3b, v46
	v_cvt_pk_bf16_f32 v50, v67, v66
	v_cvt_pk_bf16_f32 v51, v63, v64
	v_cvt_pk_bf16_f32 v52, v68, v62
	v_cvt_pk_bf16_f32 v53, v65, v69
	v_mul_f32_e32 v42, 0xbfb8aa3b, v42
	v_mul_f32_e32 v47, 0xbfb8aa3b, v47
	global_store_dwordx4 v[54:55], v[50:53], off
	v_exp_f32_e32 v46, v46
	v_exp_f32_e32 v47, v47
	v_exp_f32_e32 v50, v42
	v_fmamk_f32 v14, v30, 0x3c800000, v232
	v_fmamk_f32 v15, v31, 0x3c800000, v233
	v_fmamk_f32 v38, v38, 0x3c800000, v236
	v_fmamk_f32 v39, v39, 0x3c800000, v237
	v_fmamk_f32 v43, v43, 0x3c800000, v241
	v_med3_f32 v14, v14, s71, v172
	v_med3_f32 v15, v15, s71, v172
	v_med3_f32 v38, v38, s71, v172
	v_med3_f32 v39, v39, s71, v172
	v_med3_f32 v43, v43, s71, v172
	v_mul_f32_e32 v14, 0xbfb8aa3b, v14
	v_mul_f32_e32 v15, 0xbfb8aa3b, v15
	v_mul_f32_e32 v38, 0xbfb8aa3b, v38
	v_mul_f32_e32 v39, 0xbfb8aa3b, v39
	v_mul_f32_e32 v43, 0xbfb8aa3b, v43
	v_exp_f32_e32 v14, v14
	v_exp_f32_e32 v15, v15
	v_exp_f32_e32 v38, v38
	v_add_f32_e32 v42, 1.0, v46
	v_add_f32_e32 v46, 1.0, v50
	v_exp_f32_e32 v39, v39
	v_exp_f32_e32 v50, v43
	v_add_f32_e32 v43, 1.0, v47
	v_fmamk_f32 v10, v22, 0x3c800000, v236
	v_fmamk_f32 v6, v26, 0x3c800000, v240
	v_fmamk_f32 v11, v23, 0x3c800000, v237
	v_fmamk_f32 v7, v27, 0x3c800000, v241
	v_rcp_f32_e32 v42, v42
	v_rcp_f32_e32 v43, v43
	v_med3_f32 v10, v10, s71, v172
	v_med3_f32 v6, v6, s71, v172
	v_med3_f32 v11, v11, s71, v172
	v_med3_f32 v7, v7, s71, v172
	v_fmamk_f32 v34, v34, 0x3c800000, v244
	v_fmamk_f32 v35, v35, 0x3c800000, v245
	v_mul_f32_e32 v10, 0xbfb8aa3b, v10
	v_mul_f32_e32 v6, 0xbfb8aa3b, v6
	v_mul_f32_e32 v11, 0xbfb8aa3b, v11
	v_mul_f32_e32 v7, 0xbfb8aa3b, v7
	v_med3_f32 v34, v34, s71, v172
	v_med3_f32 v35, v35, s71, v172
	v_exp_f32_e32 v10, v10
	v_exp_f32_e32 v22, v6
	v_fmamk_f32 v2, v18, 0x3c800000, v244
	v_add_f32_e32 v6, 1.0, v14
	v_exp_f32_e32 v11, v11
	v_exp_f32_e32 v18, v7
	v_add_f32_e32 v7, 1.0, v15
	v_mul_f32_e32 v34, 0xbfb8aa3b, v34
	v_mul_f32_e32 v35, 0xbfb8aa3b, v35
	v_pk_add_f32 v[38:39], v[38:39], 1.0 op_sel_hi:[1,0]
	v_rcp_f32_e32 v6, v6
	v_rcp_f32_e32 v7, v7
	v_exp_f32_e32 v34, v34
	v_exp_f32_e32 v35, v35
	v_rcp_f32_e32 v51, v38
	v_pk_mul_f32 v[42:43], v[42:43], v[38:39]
	v_add_f32_e32 v38, 1.0, v50
	v_fmamk_f32 v3, v19, 0x3c800000, v245
	v_rcp_f32_e32 v46, v46
	v_rcp_f32_e32 v47, v38
	v_med3_f32 v2, v2, s71, v172
	v_med3_f32 v3, v3, s71, v172
	v_mul_f32_e32 v2, 0xbfb8aa3b, v2
	v_mul_f32_e32 v3, 0xbfb8aa3b, v3
	v_pk_add_f32 v[10:11], v[10:11], 1.0 op_sel_hi:[1,0]
	v_exp_f32_e32 v2, v2
	v_add_f32_e32 v14, 1.0, v22
	v_exp_f32_e32 v3, v3
	v_rcp_f32_e32 v19, v10
	v_pk_mul_f32 v[6:7], v[6:7], v[10:11]
	v_add_f32_e32 v10, 1.0, v18
	v_pk_add_f32 v[34:35], v[34:35], 1.0 op_sel_hi:[1,0]
	v_rcp_f32_e32 v14, v14
	v_rcp_f32_e32 v15, v10
	v_rcp_f32_e32 v50, v39
	v_rcp_f32_e32 v52, v34
	v_pk_mul_f32 v[38:39], v[46:47], v[34:35]
	v_fmamk_f32 v34, v48, 0x3c800000, v234
	v_med3_f32 v34, v34, s71, v172
	v_mul_f32_e32 v34, 0xbfb8aa3b, v34
	v_pk_add_f32 v[2:3], v[2:3], 1.0 op_sel_hi:[1,0]
	v_rcp_f32_e32 v46, v35
	v_exp_f32_e32 v35, v34
	v_fmamk_f32 v34, v40, 0x3c800000, v238
	v_fmamk_f32 v40, v44, 0x3c800000, v242
; __device__ __forceinline__ unsigned pk_bf16(float lo, float hi) { const f32x2_t v = {lo, hi}; return __builtin_bit_cast(unsigned, __builtin_convertvector(v, bf16x2_t)); }
;     __device__ __forceinline__ bool operator()(f32x4 (&acc)[2][2][4][2], const Unit& u, int wr, int wc, int fr, int fq) const {
;     ...
;                 for (int m = 0; m < 4; ++m) { const int row = r0 + ai * HALF + m * 16;
;                     const f32x4 a0 = acc[ai][0][m][0] * gsc + ba0, a1 = acc[ai][0][m][1] * gsc + ba1, b0 = acc[ai][1][m][0] * gsc + bb0, b1 = acc[ai][1][m][1] * gsc + bb1;
;                     f32x4 r0v, r1v, s0v, s1v;
; #pragma unroll
;                     for (int j = 0; j < 4; ++j) {
;                         const float ea0 = __builtin_amdgcn_exp2f(-1.44269504f * fminf(fmaxf(a0[j], -40.f), 40.f)), eb0 = __builtin_amdgcn_exp2f(-1.44269504f * fminf(fmaxf(b0[j], -40.f), 40.f));
;                         const float ea1 = __builtin_amdgcn_exp2f(-1.44269504f * fminf(fmaxf(a1[j], -40.f), 40.f)), eb1 = __builtin_amdgcn_exp2f(-1.44269504f * fminf(fmaxf(b1[j], -40.f), 40.f));
;                         s0v[j] = __builtin_amdgcn_rcpf(1.0f + eb0); s1v[j] = __builtin_amdgcn_rcpf(1.0f + eb1);
;                         r0v[j] = (1.0f + eb0) * __builtin_amdgcn_rcpf(1.0f + ea0); r1v[j] = (1.0f + eb1) * __builtin_amdgcn_rcpf(1.0f + ea1); }
;                     u32x4 w; w.x = pk_bf16(r0v[0], r0v[1]); w.y = pk_bf16(r0v[2], r0v[3]); w.z = pk_bf16(r1v[0], r1v[1]); w.w = pk_bf16(r1v[2], r1v[3]);
;                     *(u32x4*)(SGR + (size_t)row * D + ch0) = w;
;                     w.x = pk_bf16(s0v[0], s0v[1]); w.y = pk_bf16(s0v[2], s0v[3]); w.z = pk_bf16(s1v[0], s1v[1]); w.w = pk_bf16(s1v[2], s1v[3]);
;                     *(u32x4*)(SGB + (size_t)row * D + ch0) = w; }
	v_rcp_f32_e32 v18, v11
	v_rcp_f32_e32 v22, v2
	v_pk_mul_f32 v[10:11], v[14:15], v[2:3]
	v_fmamk_f32 v2, v32, 0x3c800000, v234
	v_med3_f32 v40, v40, s71, v172
	v_med3_f32 v2, v2, s71, v172
	v_fmamk_f32 v8, v28, 0x3c800000, v242
	v_mul_f32_e32 v40, 0xbfb8aa3b, v40
	v_mul_f32_e32 v2, 0xbfb8aa3b, v2
	v_med3_f32 v8, v8, s71, v172
	v_exp_f32_e32 v44, v40
	v_rcp_f32_e32 v14, v3
	v_exp_f32_e32 v3, v2
	v_mul_f32_e32 v8, 0xbfb8aa3b, v8
	v_fmamk_f32 v2, v24, 0x3c800000, v238
	v_exp_f32_e32 v12, v8
	v_add_f32_e32 v35, 1.0, v35
	v_rcp_f32_e32 v40, v35
	v_add_f32_e32 v35, 1.0, v44
	v_add_f32_e32 v3, 1.0, v3
	v_rcp_f32_e32 v44, v35
	v_fmamk_f32 v35, v49, 0x3c800000, v235
	v_rcp_f32_e32 v8, v3
	v_add_f32_e32 v3, 1.0, v12
	v_fmamk_f32 v17, v33, 0x3c800000, v235
	v_rcp_f32_e32 v12, v3
	v_med3_f32 v3, v17, s71, v172
	v_med3_f32 v35, v35, s71, v172
	v_mul_f32_e32 v3, 0xbfb8aa3b, v3
	v_mul_f32_e32 v35, 0xbfb8aa3b, v35
	v_exp_f32_e32 v15, v3
	v_exp_f32_e32 v47, v35
	v_fmamk_f32 v35, v41, 0x3c800000, v239
	v_fmamk_f32 v41, v45, 0x3c800000, v243
	v_fmamk_f32 v13, v25, 0x3c800000, v239
	v_fmamk_f32 v9, v29, 0x3c800000, v243
	v_med3_f32 v2, v2, s71, v172
	v_med3_f32 v3, v13, s71, v172
	v_med3_f32 v9, v9, s71, v172
	v_med3_f32 v34, v34, s71, v172
	v_med3_f32 v35, v35, s71, v172
	v_med3_f32 v41, v41, s71, v172
	v_mul_f32_e32 v2, 0xbfb8aa3b, v2
	v_mul_f32_e32 v3, 0xbfb8aa3b, v3
	v_mul_f32_e32 v9, 0xbfb8aa3b, v9
	v_mul_f32_e32 v34, 0xbfb8aa3b, v34
	v_mul_f32_e32 v35, 0xbfb8aa3b, v35
	v_mul_f32_e32 v41, 0xbfb8aa3b, v41
	v_exp_f32_e32 v2, v2
	v_exp_f32_e32 v3, v3
	v_exp_f32_e32 v13, v9
	v_add_f32_e32 v9, 1.0, v15
	v_exp_f32_e32 v34, v34
	v_fmamk_f32 v36, v36, 0x3c800000, v246
	v_exp_f32_e32 v35, v35
	v_exp_f32_e32 v45, v41
	v_fmamk_f32 v37, v37, 0x3c800000, v247
	v_add_f32_e32 v41, 1.0, v47
	v_fmamk_f32 v4, v20, 0x3c800000, v246
	v_fmamk_f32 v5, v21, 0x3c800000, v247
	v_rcp_f32_e32 v9, v9
	v_med3_f32 v36, v36, s71, v172
	v_med3_f32 v37, v37, s71, v172
	v_rcp_f32_e32 v41, v41
	v_med3_f32 v4, v4, s71, v172
	v_med3_f32 v5, v5, s71, v172
	v_mul_f32_e32 v36, 0xbfb8aa3b, v36
	v_mul_f32_e32 v37, 0xbfb8aa3b, v37
	v_mul_f32_e32 v4, 0xbfb8aa3b, v4
	v_mul_f32_e32 v5, 0xbfb8aa3b, v5
	v_exp_f32_e32 v36, v36
	v_exp_f32_e32 v37, v37
	v_exp_f32_e32 v4, v4
	v_exp_f32_e32 v5, v5
	v_pk_add_f32 v[2:3], v[2:3], 1.0 op_sel_hi:[1,0]
	v_pk_add_f32 v[34:35], v[34:35], 1.0 op_sel_hi:[1,0]
	v_rcp_f32_e32 v15, v2
	v_pk_mul_f32 v[8:9], v[8:9], v[2:3]
	v_add_f32_e32 v2, 1.0, v13
	v_rcp_f32_e32 v47, v34
	v_pk_mul_f32 v[40:41], v[40:41], v[34:35]
	v_add_f32_e32 v34, 1.0, v45
	v_rcp_f32_e32 v13, v2
	v_rcp_f32_e32 v45, v34
	v_rcp_f32_e32 v48, v35
	v_pk_add_f32 v[34:35], v[36:37], 1.0 op_sel_hi:[1,0]
	v_rcp_f32_e32 v16, v3
	v_pk_add_f32 v[2:3], v[4:5], 1.0 op_sel_hi:[1,0]
	v_rcp_f32_e32 v49, v34
	v_rcp_f32_e32 v53, v35
	v_rcp_f32_e32 v17, v2
	v_rcp_f32_e32 v20, v3
	v_cvt_pk_bf16_f32 v36, v38, v39
	v_lshl_add_u64 v[38:39], v[132:133], 0, s[34:35]
	v_pk_mul_f32 v[12:13], v[12:13], v[2:3]
	v_cvt_pk_bf16_f32 v2, v6, v7
	v_lshl_add_u64 v[6:7], v[132:133], 0, s[40:41]
	v_pk_mul_f32 v[44:45], v[44:45], v[34:35]
	v_cvt_pk_bf16_f32 v35, v40, v41
	v_lshl_add_u64 v[40:41], s[4:5], 0, v[38:39]
	v_cvt_pk_bf16_f32 v3, v8, v9
	v_lshl_add_u64 v[8:9], s[4:5], 0, v[6:7]
	v_cvt_pk_bf16_f32 v34, v42, v43
	v_cvt_pk_bf16_f32 v37, v44, v45
	v_lshl_add_u64 v[40:41], v[40:41], 0, v[130:131]
	v_lshl_add_u64 v[38:39], s[14:15], 0, v[38:39]
	v_cvt_pk_bf16_f32 v4, v10, v11
	v_cvt_pk_bf16_f32 v5, v12, v13
	v_lshl_add_u64 v[8:9], v[8:9], 0, v[130:131]
	v_lshl_add_u64 v[6:7], s[14:15], 0, v[6:7]
	global_store_dwordx4 v[40:41], v[34:37], off
	v_lshl_add_u64 v[38:39], v[38:39], 0, v[130:131]
	global_store_dwordx4 v[8:9], v[2:5], off
	v_cvt_pk_bf16_f32 v34, v51, v50
	v_cvt_pk_bf16_f32 v35, v47, v48
	v_cvt_pk_bf16_f32 v36, v52, v46
	v_cvt_pk_bf16_f32 v37, v49, v53
	v_cvt_pk_bf16_f32 v2, v19, v18
	v_cvt_pk_bf16_f32 v3, v15, v16
	v_cvt_pk_bf16_f32 v4, v22, v14
	v_cvt_pk_bf16_f32 v5, v17, v20
	v_lshl_add_u64 v[6:7], v[6:7], 0, v[130:131]
	global_store_dwordx4 v[38:39], v[34:37], off
	global_store_dwordx4 v[6:7], v[2:5], off
	s_cbranch_vccz .LBB0_730
	s_cmp_eq_u32 s101, 1
	s_cbranch_scc0 .Lnodx_p1b
	s_barrier
	s_mov_b32 s101, 0

; __device__ __forceinline__ float bf_lo(unsigned w) { return __uint_as_float(w << 16); }
; __device__ __forceinline__ float bf_hi(unsigned w) { return __uint_as_float(w & 0xffff0000u); }
;     __device__ __forceinline__ bool operator()(f32x4 (&acc)[2][2][4][2], const Unit& u, int wr, int wc, int fr, int fq) const {
;         const int r0 = u.pm * BM + wr * 64 + fr, c0 = u.pn * BM + wc * 32 + fq * 8;
;         const bf16_t* S = u.kh ? SGB : SGR;
; #pragma unroll
;         for (int ai = 0; ai < 2; ++ai)
; #pragma unroll
;             for (int m = 0; m < 4; ++m) { const size_t off = (size_t)(r0 + ai * HALF + m * 16) * D + c0;
; #pragma unroll
;                 for (int bj = 0; bj < 2; ++bj) { const u32x4 s = *(const u32x4*)(S + off + bj * HALF);
;                     f32x4 v0 = acc[ai][bj][m][0], v1 = acc[ai][bj][m][1];
;                     v0[0] *= bf_lo(s.x); v0[1] *= bf_hi(s.x); v0[2] *= bf_lo(s.y); v0[3] *= bf_hi(s.y);
;                     v1[0] *= bf_lo(s.z); v1[1] *= bf_hi(s.z); v1[2] *= bf_lo(s.w); v1[3] *= bf_hi(s.w);
;                     acc[ai][bj][m][0] = v0; acc[ai][bj][m][1] = v1; } }
.Lkepi_sa:
	s_cmp_lg_u32 s65, 0
	s_cselect_b64 s[42:43], -1, 0
	s_cmp_eq_u32 s65, 0
	s_cselect_b64 s[0:1], -1, 0
	s_and_b64 vcc, s[0:1], exec
	v_lshl_add_u32 v160, s64, 8, v1
	v_lshl_or_b32 v158, s66, 8, v173
	s_cselect_b32 s0, s5, s15
	s_cselect_b32 s1, s4, s14
	v_mov_b32_e32 v130, s1
	v_mov_b32_e32 v131, s0
	v_ashrrev_i32_e32 v159, 31, v158
	v_ashrrev_i32_e32 v161, 31, v160
	v_lshl_add_u64 v[170:171], v[158:159], 1, v[130:131]
	v_lshlrev_b64 v[130:131], 12, v[160:161]
	v_or_b32_e32 v162, 16, v160
	v_lshl_add_u64 v[130:131], v[170:171], 0, v[130:131]
	v_ashrrev_i32_e32 v163, 31, v162
	v_mov_b64_e32 v[228:229], v[130:131]
	global_load_dwordx4 v[142:145], v[130:131], off
	global_load_dwordx4 v[176:179], v[130:131], off offset:256
	v_lshlrev_b64 v[130:131], 12, v[162:163]
	v_or_b32_e32 v164, 32, v160
	v_lshl_add_u64 v[130:131], v[170:171], 0, v[130:131]
	v_ashrrev_i32_e32 v165, 31, v164
	global_load_dwordx4 v[180:183], v[130:131], off
	global_load_dwordx4 v[184:187], v[130:131], off offset:256
	v_lshlrev_b64 v[130:131], 12, v[164:165]
	v_lshl_add_u64 v[130:131], v[170:171], 0, v[130:131]
	global_load_dwordx4 v[192:195], v[130:131], off
	global_load_dwordx4 v[196:199], v[130:131], off offset:256
	v_or_b32_e32 v166, 48, v160
	v_add_u32_e32 v168, 0x80, v160
	v_ashrrev_i32_e32 v167, 31, v166
	v_ashrrev_i32_e32 v169, 31, v168
	v_lshlrev_b64 v[130:131], 12, v[166:167]
	v_lshlrev_b64 v[132:133], 12, v[168:169]
	v_lshl_add_u64 v[130:131], v[170:171], 0, v[130:131]
	v_lshl_add_u64 v[134:135], v[170:171], 0, v[132:133]
	global_load_dwordx4 v[200:203], v[130:131], off
	global_load_dwordx4 v[138:141], v[130:131], off offset:256
	s_nop 0
	global_load_dwordx4 v[130:133], v[134:135], off
	s_nop 0
	global_load_dwordx4 v[134:137], v[134:135], off offset:256
	s_mov_b64 s[0:1], 0x90000
	v_lshl_add_u64 v[226:227], v[228:229], 0, s[0:1]
	global_load_dwordx4 v[232:235], v[226:227], off
	global_load_dwordx4 v[236:239], v[226:227], off offset:256
	s_mov_b64 s[0:1], 0xa0000
	v_lshl_add_u64 v[226:227], v[228:229], 0, s[0:1]
	global_load_dwordx4 v[240:243], v[226:227], off
	global_load_dwordx4 v[244:247], v[226:227], off offset:256
	s_mov_b64 s[0:1], 0xb0000
	v_lshl_add_u64 v[226:227], v[228:229], 0, s[0:1]
	global_load_dwordx4 v[248:251], v[226:227], off
	global_load_dwordx4 v[252:255], v[226:227], off offset:256
	s_waitcnt vmcnt(0)
	v_lshlrev_b32_e32 v188, 16, v142
	v_and_b32_e32 v189, 0xffff0000, v142
	v_lshlrev_b32_e32 v142, 16, v143
	v_and_b32_e32 v143, 0xffff0000, v143
	v_pk_mul_f32 v[128:129], v[128:129], v[142:143]
	v_lshlrev_b32_e32 v204, 16, v144
	v_and_b32_e32 v205, 0xffff0000, v144
	v_lshlrev_b32_e32 v144, 16, v145
	v_lshlrev_b32_e32 v142, 16, v192
	v_and_b32_e32 v143, 0xffff0000, v192
	v_pk_mul_f32 v[110:111], v[110:111], v[142:143]
	v_lshlrev_b32_e32 v142, 16, v193
	v_and_b32_e32 v143, 0xffff0000, v193
	v_pk_mul_f32 v[112:113], v[112:113], v[142:143]
	v_add_u32_e32 v142, 0x90, v160
	v_and_b32_e32 v145, 0xffff0000, v145
	v_ashrrev_i32_e32 v143, 31, v142
	v_lshlrev_b32_e32 v210, 16, v180
	v_and_b32_e32 v211, 0xffff0000, v180
	v_lshlrev_b32_e32 v180, 16, v181
	v_and_b32_e32 v181, 0xffff0000, v181
	v_pk_mul_f32 v[124:125], v[124:125], v[144:145]
	v_lshlrev_b64 v[144:145], 12, v[142:143]
	v_lshlrev_b32_e32 v206, 16, v176
	v_and_b32_e32 v207, 0xffff0000, v176
	v_lshlrev_b32_e32 v176, 16, v177
	v_and_b32_e32 v177, 0xffff0000, v177
	v_lshlrev_b32_e32 v208, 16, v178
	v_and_b32_e32 v209, 0xffff0000, v178
	v_lshlrev_b32_e32 v178, 16, v179
	v_and_b32_e32 v179, 0xffff0000, v179
	v_pk_mul_f32 v[120:121], v[120:121], v[180:181]
	v_lshl_add_u64 v[144:145], v[170:171], 0, v[144:145]
	v_lshlrev_b32_e32 v180, 16, v194
	v_and_b32_e32 v181, 0xffff0000, v194
	v_pk_mul_f32 v[96:97], v[96:97], v[176:177]
	v_pk_mul_f32 v[92:93], v[92:93], v[178:179]
	v_mov_b64_e32 v[176:177], v[232:233]
	v_mov_b64_e32 v[178:179], v[234:235]
	v_pk_mul_f32 v[106:107], v[106:107], v[180:181]
	v_lshlrev_b32_e32 v180, 16, v195
	v_and_b32_e32 v181, 0xffff0000, v195
	v_lshlrev_b32_e32 v212, 16, v182
	v_and_b32_e32 v213, 0xffff0000, v182
	v_lshlrev_b32_e32 v182, 16, v183
	v_and_b32_e32 v183, 0xffff0000, v183
	v_pk_mul_f32 v[108:109], v[108:109], v[180:181]
	v_lshlrev_b32_e32 v180, 16, v196
	v_and_b32_e32 v181, 0xffff0000, v196
	v_pk_mul_f32 v[116:117], v[116:117], v[182:183]
	v_pk_mul_f32 v[78:79], v[78:79], v[180:181]
	v_mov_b64_e32 v[180:181], v[236:237]
	v_mov_b64_e32 v[182:183], v[238:239]
	v_lshlrev_b32_e32 v144, 16, v198
	v_and_b32_e32 v145, 0xffff0000, v198
	v_pk_mul_f32 v[74:75], v[74:75], v[144:145]
	v_lshlrev_b32_e32 v144, 16, v199
	v_and_b32_e32 v145, 0xffff0000, v199
	v_lshlrev_b32_e32 v214, 16, v184
	v_and_b32_e32 v215, 0xffff0000, v184
	v_lshlrev_b32_e32 v184, 16, v185
	v_and_b32_e32 v185, 0xffff0000, v185
	v_pk_mul_f32 v[76:77], v[76:77], v[144:145]
	v_add_u32_e32 v144, 0xa0, v160
	v_pk_mul_f32 v[88:89], v[88:89], v[184:185]
	v_lshlrev_b32_e32 v184, 16, v197
	v_and_b32_e32 v185, 0xffff0000, v197
	v_ashrrev_i32_e32 v145, 31, v144
	v_pk_mul_f32 v[80:81], v[80:81], v[184:185]
	v_lshlrev_b64 v[184:185], 12, v[144:145]
	v_lshlrev_b32_e32 v216, 16, v186
	v_and_b32_e32 v217, 0xffff0000, v186
	v_lshlrev_b32_e32 v186, 16, v187
	v_and_b32_e32 v187, 0xffff0000, v187
	v_pk_mul_f32 v[126:127], v[126:127], v[188:189]
	v_lshl_add_u64 v[188:189], v[170:171], 0, v[184:185]
	v_pk_mul_f32 v[84:85], v[84:85], v[186:187]
	v_mov_b64_e32 v[184:185], v[240:241]
	v_mov_b64_e32 v[186:187], v[242:243]
	v_lshlrev_b32_e32 v192, 16, v200
	v_and_b32_e32 v193, 0xffff0000, v200
	v_pk_mul_f32 v[102:103], v[102:103], v[192:193]
	v_lshlrev_b32_e32 v192, 16, v201
	v_and_b32_e32 v193, 0xffff0000, v201
; __device__ __forceinline__ float bf_lo(unsigned w) { return __uint_as_float(w << 16); }
; __device__ __forceinline__ float bf_hi(unsigned w) { return __uint_as_float(w & 0xffff0000u); }
;     __device__ __forceinline__ bool operator()(f32x4 (&acc)[2][2][4][2], const Unit& u, int wr, int wc, int fr, int fq) const {
;     ...
;                 for (int bj = 0; bj < 2; ++bj) { const u32x4 s = *(const u32x4*)(S + off + bj * HALF);
;                     f32x4 v0 = acc[ai][bj][m][0], v1 = acc[ai][bj][m][1];
;                     v0[0] *= bf_lo(s.x); v0[1] *= bf_hi(s.x); v0[2] *= bf_lo(s.y); v0[3] *= bf_hi(s.y);
;                     v1[0] *= bf_lo(s.z); v1[1] *= bf_hi(s.z); v1[2] *= bf_lo(s.w); v1[3] *= bf_hi(s.w);
;                     acc[ai][bj][m][0] = v0; acc[ai][bj][m][1] = v1; } }
	v_pk_mul_f32 v[104:105], v[104:105], v[192:193]
	v_lshlrev_b32_e32 v192, 16, v202
	v_and_b32_e32 v193, 0xffff0000, v202
	v_pk_mul_f32 v[98:99], v[98:99], v[192:193]
	v_mov_b64_e32 v[192:193], v[244:245]
	v_mov_b64_e32 v[194:195], v[246:247]
	v_lshlrev_b32_e32 v188, 16, v138
	v_and_b32_e32 v189, 0xffff0000, v138
	v_lshlrev_b32_e32 v138, 16, v139
	v_and_b32_e32 v139, 0xffff0000, v139
	v_pk_mul_f32 v[72:73], v[72:73], v[138:139]
	v_add_u32_e32 v138, 0xb0, v160
	v_ashrrev_i32_e32 v139, 31, v138
	v_pk_mul_f32 v[70:71], v[70:71], v[188:189]
	v_lshlrev_b64 v[188:189], 12, v[138:139]
	v_lshlrev_b32_e32 v196, 16, v203
	v_and_b32_e32 v197, 0xffff0000, v203
	v_lshl_add_u64 v[170:171], v[170:171], 0, v[188:189]
	v_pk_mul_f32 v[100:101], v[100:101], v[196:197]
	v_mov_b64_e32 v[196:197], v[248:249]
	v_mov_b64_e32 v[198:199], v[250:251]
	v_mov_b64_e32 v[200:201], v[252:253]
	v_mov_b64_e32 v[202:203], v[254:255]
	v_lshlrev_b32_e32 v188, 16, v140
	v_and_b32_e32 v189, 0xffff0000, v140
	v_lshlrev_b32_e32 v140, 16, v141
	v_and_b32_e32 v141, 0xffff0000, v141
	v_pk_mul_f32 v[68:69], v[68:69], v[140:141]
	v_lshlrev_b32_e32 v140, 16, v130
	v_and_b32_e32 v141, 0xffff0000, v130
	v_lshlrev_b32_e32 v130, 16, v131
	v_and_b32_e32 v131, 0xffff0000, v131
	v_pk_mul_f32 v[64:65], v[64:65], v[130:131]
	v_lshlrev_b32_e32 v130, 16, v132
	v_and_b32_e32 v131, 0xffff0000, v132
	v_pk_mul_f32 v[58:59], v[58:59], v[130:131]
	v_lshlrev_b32_e32 v130, 16, v133
	v_and_b32_e32 v131, 0xffff0000, v133
	v_pk_mul_f32 v[60:61], v[60:61], v[130:131]
	v_lshlrev_b32_e32 v130, 16, v134
	v_and_b32_e32 v131, 0xffff0000, v134
	v_pk_mul_f32 v[30:31], v[30:31], v[130:131]
	v_lshlrev_b32_e32 v130, 16, v135
	v_and_b32_e32 v131, 0xffff0000, v135
	v_pk_mul_f32 v[32:33], v[32:33], v[130:131]
	v_lshlrev_b32_e32 v130, 16, v136
	v_and_b32_e32 v131, 0xffff0000, v136
	v_pk_mul_f32 v[26:27], v[26:27], v[130:131]
	v_lshlrev_b32_e32 v130, 16, v137
	v_and_b32_e32 v131, 0xffff0000, v137
	v_pk_mul_f32 v[28:29], v[28:29], v[130:131]
	s_waitcnt vmcnt(0)
	v_lshlrev_b32_e32 v130, 16, v176
	v_and_b32_e32 v131, 0xffff0000, v176
	v_pk_mul_f32 v[54:55], v[54:55], v[130:131]
	v_lshlrev_b32_e32 v130, 16, v177
	v_and_b32_e32 v131, 0xffff0000, v177
	v_pk_mul_f32 v[56:57], v[56:57], v[130:131]
	v_lshlrev_b32_e32 v130, 16, v178
	v_and_b32_e32 v131, 0xffff0000, v178
	v_pk_mul_f32 v[50:51], v[50:51], v[130:131]
	v_lshlrev_b32_e32 v130, 16, v179
	v_and_b32_e32 v131, 0xffff0000, v179
	v_pk_mul_f32 v[52:53], v[52:53], v[130:131]
	v_lshlrev_b32_e32 v130, 16, v180
	v_and_b32_e32 v131, 0xffff0000, v180
	v_pk_mul_f32 v[22:23], v[22:23], v[130:131]
	v_lshlrev_b32_e32 v130, 16, v181
	v_and_b32_e32 v131, 0xffff0000, v181
	v_pk_mul_f32 v[24:25], v[24:25], v[130:131]
	v_lshlrev_b32_e32 v130, 16, v182
	v_and_b32_e32 v131, 0xffff0000, v182
	v_pk_mul_f32 v[18:19], v[18:19], v[130:131]
	v_lshlrev_b32_e32 v130, 16, v183
	v_and_b32_e32 v131, 0xffff0000, v183
	v_pk_mul_f32 v[20:21], v[20:21], v[130:131]
	v_pk_mul_f32 v[122:123], v[122:123], v[204:205]
	v_pk_mul_f32 v[94:95], v[94:95], v[206:207]
	v_lshlrev_b32_e32 v130, 16, v184
	v_and_b32_e32 v131, 0xffff0000, v184
	v_pk_mul_f32 v[46:47], v[46:47], v[130:131]
	v_lshlrev_b32_e32 v130, 16, v185
	v_and_b32_e32 v131, 0xffff0000, v185
	v_pk_mul_f32 v[48:49], v[48:49], v[130:131]
	v_lshlrev_b32_e32 v130, 16, v186
	v_and_b32_e32 v131, 0xffff0000, v186
	v_pk_mul_f32 v[42:43], v[42:43], v[130:131]
	v_lshlrev_b32_e32 v130, 16, v187
	v_and_b32_e32 v131, 0xffff0000, v187
	v_pk_mul_f32 v[44:45], v[44:45], v[130:131]
	v_lshlrev_b32_e32 v130, 16, v192
	v_and_b32_e32 v131, 0xffff0000, v192
	v_pk_mul_f32 v[14:15], v[14:15], v[130:131]
	v_lshlrev_b32_e32 v130, 16, v193
	v_and_b32_e32 v131, 0xffff0000, v193
	v_pk_mul_f32 v[16:17], v[16:17], v[130:131]
	v_lshlrev_b32_e32 v130, 16, v194
	v_and_b32_e32 v131, 0xffff0000, v194
	v_pk_mul_f32 v[10:11], v[10:11], v[130:131]
	v_lshlrev_b32_e32 v130, 16, v195
	v_and_b32_e32 v131, 0xffff0000, v195
	v_pk_mul_f32 v[12:13], v[12:13], v[130:131]
	v_lshlrev_b32_e32 v130, 16, v196
	v_and_b32_e32 v131, 0xffff0000, v196
	v_pk_mul_f32 v[38:39], v[38:39], v[130:131]
	v_lshlrev_b32_e32 v130, 16, v197
	v_and_b32_e32 v131, 0xffff0000, v197
	v_pk_mul_f32 v[40:41], v[40:41], v[130:131]
	v_lshlrev_b32_e32 v130, 16, v198
	v_and_b32_e32 v131, 0xffff0000, v198
	v_pk_mul_f32 v[34:35], v[34:35], v[130:131]
	v_lshlrev_b32_e32 v130, 16, v199
	v_and_b32_e32 v131, 0xffff0000, v199
	v_pk_mul_f32 v[36:37], v[36:37], v[130:131]
	v_lshlrev_b32_e32 v130, 16, v200
	v_and_b32_e32 v131, 0xffff0000, v200
	v_pk_mul_f32 v[6:7], v[6:7], v[130:131]
	v_lshlrev_b32_e32 v130, 16, v201
	v_and_b32_e32 v131, 0xffff0000, v201
	v_pk_mul_f32 v[8:9], v[8:9], v[130:131]
	v_lshlrev_b32_e32 v130, 16, v202
	v_and_b32_e32 v131, 0xffff0000, v202
	v_pk_mul_f32 v[2:3], v[2:3], v[130:131]
	v_lshlrev_b32_e32 v130, 16, v203
	v_and_b32_e32 v131, 0xffff0000, v203
	v_pk_mul_f32 v[90:91], v[90:91], v[208:209]
	v_pk_mul_f32 v[118:119], v[118:119], v[210:211]
	v_pk_mul_f32 v[114:115], v[114:115], v[212:213]
	v_pk_mul_f32 v[86:87], v[86:87], v[214:215]
	v_pk_mul_f32 v[82:83], v[82:83], v[216:217]
	v_pk_mul_f32 v[66:67], v[66:67], v[188:189]
	v_pk_mul_f32 v[62:63], v[62:63], v[140:141]
	v_pk_mul_f32 v[4:5], v[4:5], v[130:131]
	s_cbranch_vccnz .LBB0_818
; __device__ __forceinline__ unsigned pk_bf16(float lo, float hi) { const f32x2_t v = {lo, hi}; return __builtin_bit_cast(unsigned, __builtin_convertvector(v, bf16x2_t)); }
;     __device__ __forceinline__ bool operator()(f32x4 (&acc)[2][2][4][2], const Unit& u, int wr, int wc, int fr, int fq) const {
;     ...
; #pragma unroll
;         for (int ai = 0; ai < 2; ++ai)
; #pragma unroll
;             for (int m = 0; m < 4; ++m) { const size_t off = (size_t)(r0 + ai * HALF + m * 16) * LDP + c0;
; #pragma unroll
;                 for (int bj = 0; bj < 2; ++bj) { const f32x4 v0 = acc[ai][bj][m][0], v1 = acc[ai][bj][m][1];
;                     u32x4 w; w.x = pk_bf16(v0[0], v0[1]); w.y = pk_bf16(v0[2], v0[3]); w.z = pk_bf16(v1[0], v1[1]); w.w = pk_bf16(v1[2], v1[3]);
;                     *(u32x4*)(MG + off + bj * HALF) = w; } }
	v_mov_b64_e32 v[134:135], s[12:13]
	v_mad_i64_i32 v[136:137], s[0:1], v160, s60, v[134:135]
	v_lshlrev_b64 v[140:141], 1, v[158:159]
	v_cvt_pk_bf16_f32 v130, v126, v127
	v_cvt_pk_bf16_f32 v131, v128, v129
	v_cvt_pk_bf16_f32 v132, v122, v123
	v_cvt_pk_bf16_f32 v133, v124, v125
	v_lshl_add_u64 v[136:137], v[136:137], 0, v[140:141]
	global_store_dwordx4 v[136:137], v[130:133], off
	s_nop 1
	v_cvt_pk_bf16_f32 v130, v94, v95
	v_cvt_pk_bf16_f32 v131, v96, v97
	v_cvt_pk_bf16_f32 v132, v90, v91
	v_cvt_pk_bf16_f32 v133, v92, v93
	global_store_dwordx4 v[136:137], v[130:133], off offset:256
	v_mad_i64_i32 v[136:137], s[0:1], v162, s60, v[134:135]
	s_nop 0
	v_cvt_pk_bf16_f32 v130, v118, v119
	v_cvt_pk_bf16_f32 v131, v120, v121
	v_cvt_pk_bf16_f32 v132, v114, v115
	v_cvt_pk_bf16_f32 v133, v116, v117
	v_lshl_add_u64 v[136:137], v[136:137], 0, v[140:141]
	global_store_dwordx4 v[136:137], v[130:133], off
	s_nop 1
	v_cvt_pk_bf16_f32 v130, v86, v87
	v_cvt_pk_bf16_f32 v131, v88, v89
	v_cvt_pk_bf16_f32 v132, v82, v83
	v_cvt_pk_bf16_f32 v133, v84, v85
	global_store_dwordx4 v[136:137], v[130:133], off offset:256
	v_mad_i64_i32 v[136:137], s[0:1], v164, s60, v[134:135]
	s_nop 0
	v_cvt_pk_bf16_f32 v130, v110, v111
	v_cvt_pk_bf16_f32 v131, v112, v113
	v_cvt_pk_bf16_f32 v132, v106, v107
	v_cvt_pk_bf16_f32 v133, v108, v109
	v_lshl_add_u64 v[136:137], v[136:137], 0, v[140:141]
	global_store_dwordx4 v[136:137], v[130:133], off
	s_nop 1
	v_cvt_pk_bf16_f32 v130, v78, v79
	v_cvt_pk_bf16_f32 v131, v80, v81
	v_cvt_pk_bf16_f32 v132, v74, v75
	v_cvt_pk_bf16_f32 v133, v76, v77
	global_store_dwordx4 v[136:137], v[130:133], off offset:256
	v_mad_i64_i32 v[136:137], s[0:1], v166, s60, v[134:135]
	s_nop 0
	v_cvt_pk_bf16_f32 v130, v102, v103
	v_cvt_pk_bf16_f32 v131, v104, v105
	v_cvt_pk_bf16_f32 v132, v98, v99
	v_cvt_pk_bf16_f32 v133, v100, v101
	v_lshl_add_u64 v[136:137], v[136:137], 0, v[140:141]
	global_store_dwordx4 v[136:137], v[130:133], off
	s_nop 1
	v_cvt_pk_bf16_f32 v130, v70, v71
	v_cvt_pk_bf16_f32 v131, v72, v73
	v_cvt_pk_bf16_f32 v132, v66, v67
	v_cvt_pk_bf16_f32 v133, v68, v69
	global_store_dwordx4 v[136:137], v[130:133], off offset:256
	v_mad_i64_i32 v[136:137], s[0:1], v168, s60, v[134:135]
	s_nop 0
	v_cvt_pk_bf16_f32 v130, v62, v63
	v_cvt_pk_bf16_f32 v131, v64, v65
	v_cvt_pk_bf16_f32 v132, v58, v59
	v_cvt_pk_bf16_f32 v133, v60, v61
	v_lshl_add_u64 v[136:137], v[136:137], 0, v[140:141]
	global_store_dwordx4 v[136:137], v[130:133], off
	s_nop 1
	v_cvt_pk_bf16_f32 v130, v30, v31
	v_cvt_pk_bf16_f32 v131, v32, v33
	v_cvt_pk_bf16_f32 v132, v26, v27
	v_cvt_pk_bf16_f32 v133, v28, v29
	global_store_dwordx4 v[136:137], v[130:133], off offset:256
	v_mad_i64_i32 v[136:137], s[0:1], v142, s60, v[134:135]
	s_nop 0
	v_cvt_pk_bf16_f32 v130, v54, v55
	v_cvt_pk_bf16_f32 v131, v56, v57
	v_cvt_pk_bf16_f32 v132, v50, v51
	v_cvt_pk_bf16_f32 v133, v52, v53
	v_lshl_add_u64 v[136:137], v[136:137], 0, v[140:141]
	global_store_dwordx4 v[136:137], v[130:133], off
	s_nop 1
	v_cvt_pk_bf16_f32 v130, v22, v23
	v_cvt_pk_bf16_f32 v131, v24, v25
	v_cvt_pk_bf16_f32 v132, v18, v19
	v_cvt_pk_bf16_f32 v133, v20, v21
	global_store_dwordx4 v[136:137], v[130:133], off offset:256
	v_mad_i64_i32 v[136:137], s[0:1], v144, s60, v[134:135]
	s_nop 0
	v_cvt_pk_bf16_f32 v130, v46, v47
	v_cvt_pk_bf16_f32 v131, v48, v49
	v_cvt_pk_bf16_f32 v132, v42, v43
	v_cvt_pk_bf16_f32 v133, v44, v45
	v_lshl_add_u64 v[136:137], v[136:137], 0, v[140:141]
	global_store_dwordx4 v[136:137], v[130:133], off
	v_mad_i64_i32 v[134:135], s[0:1], v138, s60, v[134:135]
	s_nop 0
	v_cvt_pk_bf16_f32 v130, v14, v15
	v_cvt_pk_bf16_f32 v131, v16, v17
	v_cvt_pk_bf16_f32 v132, v10, v11
	v_cvt_pk_bf16_f32 v133, v12, v13
	global_store_dwordx4 v[136:137], v[130:133], off offset:256
	v_lshl_add_u64 v[134:135], v[134:135], 0, v[140:141]
	s_nop 0
	v_cvt_pk_bf16_f32 v130, v38, v39
	v_cvt_pk_bf16_f32 v131, v40, v41
	v_cvt_pk_bf16_f32 v132, v34, v35
	v_cvt_pk_bf16_f32 v133, v36, v37
	global_store_dwordx4 v[134:135], v[130:133], off
	s_nop 1
	v_cvt_pk_bf16_f32 v130, v6, v7
	v_cvt_pk_bf16_f32 v131, v8, v9
	v_cvt_pk_bf16_f32 v132, v2, v3
	v_cvt_pk_bf16_f32 v133, v4, v5
	global_store_dwordx4 v[134:135], v[130:133], off offset:256
